# S5 items: B operands fetched as 32-byte dwordx4 pieces
# speedup vs baseline: 1.2989x; 1.0046x over previous
; __device__ __forceinline__ int otid() { int t = threadIdx.x; asm volatile("" : "+v"(t)); return t; }
; __device__ void phase_s5_pass1(CParams& p, int l, int item, char* smem) {
;   const int tid = otid(), lane = tid & 63, wid = tid >> 6;
;   int q = item >> 3, dir = (item >> 2) & 1, gq = item & 3;
;   int g = gq * 4 + wid;
;   float* us = (float*)smem + wid * 1024;
;   int tok0 = q * 64;
;   __syncthreads();
;   {
;     const float* src = p.zs5 + (size_t)(tok0 + lane) * 256 + g * 16;
; #pragma unroll
;     for (int i = 0; i < 4; i++) *(float4*)(us + lane * 16 + i * 4) = *(const float4*)(src + i * 4);
;   }
;   int pidx = ((l * 2 + dir) * 16 + g) * 64 + lane;
;   float2 A = p.Apar[pidx];
;   f32x2 bb[16];
; #pragma unroll
;   for (int cc = 0; cc < 16; cc++) {
;     float2 b = p.Bbar[(size_t)pidx * 16 + cc];
;     bb[cc] = f32x2{b.x, b.y};
;   }
;   __syncthreads();
;   float hr = 0.f, hi = 0.f;
;   for (int i = 0; i < 64; i++) {
;     int t = dir == 0 ? i : 63 - i;
;     float u[16];
; #pragma unroll
;     for (int k = 0; k < 4; k++) {
;       float4 uv = *(const float4*)(us + t * 16 + k * 4);
;       u[k * 4] = uv.x; u[k * 4 + 1] = uv.y; u[k * 4 + 2] = uv.z; u[k * 4 + 3] = uv.w;
;     }
;     f32x2 bu = {0.f, 0.f};
; #pragma unroll
;     for (int cc = 0; cc < 16; cc++) bu = __builtin_elementwise_fma(bb[cc], f32x2{u[cc], u[cc]}, bu);
.LBB0_379:
	s_cmpk_gt_i32 s29, 0x1ff
	s_mov_b64 s[26:27], -1
	s_mov_b32 s1, 0xffff0000
	s_mov_b32 s16, 0x8000
	s_cbranch_scc0 .LBB0_387
	s_cmpk_gt_u32 s29, 0x27f
	s_cbranch_scc0 .LBB0_384
	s_add_i32 s2, s29, 0xfffffd80
	v_readfirstlane_b32 s32, v147
	v_and_b32_e32 v32, 63, v147
	s_lshr_b32 s4, s2, 3
	s_lshr_b32 s10, s2, 2
	s_and_b32 s10, s10, 1
	s_and_b32 s17, s2, 3
	s_lshl_b32 s17, s17, 2
	s_lshr_b32 s32, s32, 6
	s_add_u32 s17, s17, s32
	s_lshl_b32 s0, s10, 4
	s_add_u32 s0, s0, s28
	s_add_u32 s0, s0, s17
	s_lshl_b32 s33, s0, 6
	s_lshl_b32 s0, s33, 3
	s_add_u32 s6, s48, s0
	s_addc_u32 s7, s49, 0
	s_lshl_b32 s0, s33, 7
	s_add_u32 s8, s50, s0
	s_addc_u32 s9, s51, 0
	s_lshl_b32 s0, s4, 16
	s_lshl_b32 s62, s17, 6
	s_add_u32 s0, s0, s62
	s_add_u32 s12, s42, s0
	s_addc_u32 s13, s43, 0
	s_lshl_b32 s0, s4, 1
	s_add_u32 s0, s0, s10
	s_lshl_b32 s0, s0, 4
	s_add_u32 s0, s0, s17
	s_lshl_b32 s0, s0, 9
	s_add_u32 s18, s20, s0
	s_addc_u32 s19, s21, 0
	s_lshl_b32 s93, s32, 14
	s_cmp_ge_u32 s32, 2
	s_cselect_b32 s0, 0x4000, 0
	s_add_u32 s93, s93, s0
	v_and_b32_e32 v33, 15, v32
	v_lshrrev_b32_e32 v34, 4, v32
	v_lshlrev_b32_e32 v38, 3, v32
	global_load_dwordx2 v[36:37], v38, s[6:7]
	v_lshlrev_b32_e32 v40, 7, v33
	v_lshl_add_u32 v40, v34, 5, v40
	v_add_u32_e32 v41, 0x1000, v40
	global_load_dwordx4 v[64:67], v40, s[8:9] offset:0
	global_load_dwordx4 v[68:71], v40, s[8:9] offset:16
	global_load_dwordx4 v[72:75], v40, s[8:9] offset:2048
	global_load_dwordx4 v[76:79], v40, s[8:9] offset:2064
	global_load_dwordx4 v[80:83], v41, s[8:9] offset:0
	global_load_dwordx4 v[84:87], v41, s[8:9] offset:16
	global_load_dwordx4 v[88:91], v41, s[8:9] offset:2048
	global_load_dwordx4 v[92:95], v41, s[8:9] offset:2064
	v_sub_u32_e32 v38, 63, v33
	s_mov_b32 s92, 0xffffc000
	s_cmp_eq_u32 s10, 0
	s_cselect_b64 vcc, -1, 0
	s_nop 1
	v_cndmask_b32_e32 v38, v38, v33, vcc
	v_lshlrev_b32_e32 v42, 10, v38
	v_lshl_add_u32 v42, v34, 4, v42
	s_cselect_b32 s92, 0x4000, s92
	global_load_dwordx4 v[96:99], v42, s[12:13]
	v_add_u32_e32 v42, s92, v42
	global_load_dwordx4 v[100:103], v42, s[12:13]
	v_add_u32_e32 v42, s92, v42
	global_load_dwordx4 v[104:107], v42, s[12:13]
	v_add_u32_e32 v42, s92, v42
	global_load_dwordx4 v[108:111], v42, s[12:13]
	v_lshlrev_b32_e32 v38, 11, v34
	v_lshl_add_u32 v38, v33, 3, v38
	v_add_u32_e32 v38, s93, v38
	v_add_u32_e32 v44, 0x0, v38
	v_add_u32_e32 v45, 0x200, v38
	v_add_u32_e32 v46, 0x400, v38
	v_add_u32_e32 v47, 0x600, v38
	v_add_u32_e32 v48, 0x2000, v38
	v_add_u32_e32 v49, 0x2200, v38
	v_add_u32_e32 v50, 0x2400, v38
	v_add_u32_e32 v51, 0x2600, v38
	v_lshlrev_b32_e32 v52, 3, v32
	v_add_u32_e32 v52, s93, v52
	v_mov_b32_e32 v54, 0
	v_mov_b32_e32 v55, 0
	s_barrier
	s_waitcnt vmcnt(3)
	v_mfma_f32_16x16x4_f32 v[0:3], v96, v64, 0
	v_mfma_f32_16x16x4_f32 v[4:7], v96, v65, 0
	v_mfma_f32_16x16x4_f32 v[8:11], v96, v72, 0
	v_mfma_f32_16x16x4_f32 v[12:15], v96, v73, 0
	v_mfma_f32_16x16x4_f32 v[16:19], v96, v80, 0
	v_mfma_f32_16x16x4_f32 v[20:23], v96, v81, 0
	v_mfma_f32_16x16x4_f32 v[24:27], v96, v88, 0
	v_mfma_f32_16x16x4_f32 v[28:31], v96, v89, 0
	v_mfma_f32_16x16x4_f32 v[0:3], v97, v66, v[0:3]
	v_mfma_f32_16x16x4_f32 v[4:7], v97, v67, v[4:7]
	v_mfma_f32_16x16x4_f32 v[8:11], v97, v74, v[8:11]
	v_mfma_f32_16x16x4_f32 v[12:15], v97, v75, v[12:15]
	v_mfma_f32_16x16x4_f32 v[16:19], v97, v82, v[16:19]
	v_mfma_f32_16x16x4_f32 v[20:23], v97, v83, v[20:23]
	v_mfma_f32_16x16x4_f32 v[24:27], v97, v90, v[24:27]
	v_mfma_f32_16x16x4_f32 v[28:31], v97, v91, v[28:31]
	v_mfma_f32_16x16x4_f32 v[0:3], v98, v68, v[0:3]
	v_mfma_f32_16x16x4_f32 v[4:7], v98, v69, v[4:7]
	v_mfma_f32_16x16x4_f32 v[8:11], v98, v76, v[8:11]
	v_mfma_f32_16x16x4_f32 v[12:15], v98, v77, v[12:15]
	v_mfma_f32_16x16x4_f32 v[16:19], v98, v84, v[16:19]
	v_mfma_f32_16x16x4_f32 v[20:23], v98, v85, v[20:23]
	v_mfma_f32_16x16x4_f32 v[24:27], v98, v92, v[24:27]
	v_mfma_f32_16x16x4_f32 v[28:31], v98, v93, v[28:31]
	v_mfma_f32_16x16x4_f32 v[0:3], v99, v70, v[0:3]
	v_mfma_f32_16x16x4_f32 v[4:7], v99, v71, v[4:7]
	v_mfma_f32_16x16x4_f32 v[8:11], v99, v78, v[8:11]
	v_mfma_f32_16x16x4_f32 v[12:15], v99, v79, v[12:15]
	v_mfma_f32_16x16x4_f32 v[16:19], v99, v86, v[16:19]
	v_mfma_f32_16x16x4_f32 v[20:23], v99, v87, v[20:23]
	v_mfma_f32_16x16x4_f32 v[24:27], v99, v94, v[24:27]
	v_mfma_f32_16x16x4_f32 v[28:31], v99, v95, v[28:31]
	s_nop 15
	s_nop 15
	ds_write2_b32 v44, v0, v4 offset0:0 offset1:1
	ds_write2_b32 v45, v1, v5 offset0:0 offset1:1
	ds_write2_b32 v46, v2, v6 offset0:0 offset1:1
	ds_write2_b32 v47, v3, v7 offset0:0 offset1:1
	ds_write2_b32 v44, v8, v12 offset0:32 offset1:33
	ds_write2_b32 v45, v9, v13 offset0:32 offset1:33
	ds_write2_b32 v46, v10, v14 offset0:32 offset1:33
	ds_write2_b32 v47, v11, v15 offset0:32 offset1:33
	ds_write2_b32 v44, v16, v20 offset0:64 offset1:65
	ds_write2_b32 v45, v17, v21 offset0:64 offset1:65
	ds_write2_b32 v46, v18, v22 offset0:64 offset1:65
	ds_write2_b32 v47, v19, v23 offset0:64 offset1:65
	ds_write2_b32 v44, v24, v28 offset0:96 offset1:97
	ds_write2_b32 v45, v25, v29 offset0:96 offset1:97
	ds_write2_b32 v46, v26, v30 offset0:96 offset1:97
	ds_write2_b32 v47, v27, v31 offset0:96 offset1:97
	ds_read_b64 v[0:1], v52 offset:0
	ds_read_b64 v[2:3], v52 offset:512
	ds_read_b64 v[4:5], v52 offset:1024
	ds_read_b64 v[6:7], v52 offset:1536
	ds_read_b64 v[8:9], v52 offset:2048
	ds_read_b64 v[10:11], v52 offset:2560
	ds_read_b64 v[12:13], v52 offset:3072
	ds_read_b64 v[14:15], v52 offset:3584
	ds_read_b64 v[16:17], v52 offset:4096
	ds_read_b64 v[18:19], v52 offset:4608
	ds_read_b64 v[20:21], v52 offset:5120
	ds_read_b64 v[22:23], v52 offset:5632
	ds_read_b64 v[24:25], v52 offset:6144
	ds_read_b64 v[26:27], v52 offset:6656
	ds_read_b64 v[28:29], v52 offset:7168
	ds_read_b64 v[30:31], v52 offset:7680
	s_waitcnt vmcnt(2)
; __device__ void phase_s5_pass1(CParams& p, int l, int item, char* smem) {
;     ...
;   for (int i = 0; i < 64; i++) {
;     int t = dir == 0 ? i : 63 - i;
;     float u[16];
; #pragma unroll
;     for (int k = 0; k < 4; k++) {
;       float4 uv = *(const float4*)(us + t * 16 + k * 4);
;       u[k * 4] = uv.x; u[k * 4 + 1] = uv.y; u[k * 4 + 2] = uv.z; u[k * 4 + 3] = uv.w;
;     }
;     f32x2 bu = {0.f, 0.f};
; #pragma unroll
;     for (int cc = 0; cc < 16; cc++) bu = __builtin_elementwise_fma(bb[cc], f32x2{u[cc], u[cc]}, bu);
;     float nr = A.x * hr - A.y * hi + bu[0];
;     float ni = A.x * hi + A.y * hr + bu[1];
;     hr = nr; hi = ni;
	s_waitcnt lgkmcnt(15)
	v_fma_f32 v58, v36, v54, v0
	v_fma_f32 v59, v36, v55, v1
	v_mfma_f32_16x16x4_f32 v[112:115], v100, v64, 0
	v_mfma_f32_16x16x4_f32 v[116:119], v100, v65, 0
	v_fma_f32 v56, -v37, v55, v58
	v_fma_f32 v57, v37, v54, v59
	s_waitcnt lgkmcnt(14)
	v_fma_f32 v58, v36, v56, v2
	v_fma_f32 v59, v36, v57, v3
	v_mfma_f32_16x16x4_f32 v[120:123], v100, v72, 0
	v_mfma_f32_16x16x4_f32 v[124:127], v100, v73, 0
	v_fma_f32 v54, -v37, v57, v58
	v_fma_f32 v55, v37, v56, v59
	s_waitcnt lgkmcnt(13)
	v_fma_f32 v58, v36, v54, v4
	v_fma_f32 v59, v36, v55, v5
	v_mfma_f32_16x16x4_f32 v[128:131], v100, v80, 0
	v_mfma_f32_16x16x4_f32 v[132:135], v100, v81, 0
	v_fma_f32 v56, -v37, v55, v58
	v_fma_f32 v57, v37, v54, v59
	s_waitcnt lgkmcnt(12)
	v_fma_f32 v58, v36, v56, v6
	v_fma_f32 v59, v36, v57, v7
	v_mfma_f32_16x16x4_f32 v[136:139], v100, v88, 0
	v_mfma_f32_16x16x4_f32 v[140:143], v100, v89, 0
	v_fma_f32 v54, -v37, v57, v58
	v_fma_f32 v55, v37, v56, v59
	s_waitcnt lgkmcnt(11)
	v_fma_f32 v58, v36, v54, v8
	v_fma_f32 v59, v36, v55, v9
	v_mfma_f32_16x16x4_f32 v[112:115], v101, v66, v[112:115]
	v_mfma_f32_16x16x4_f32 v[116:119], v101, v67, v[116:119]
	v_fma_f32 v56, -v37, v55, v58
	v_fma_f32 v57, v37, v54, v59
	s_waitcnt lgkmcnt(10)
	v_fma_f32 v58, v36, v56, v10
	v_fma_f32 v59, v36, v57, v11
	v_mfma_f32_16x16x4_f32 v[120:123], v101, v74, v[120:123]
	v_mfma_f32_16x16x4_f32 v[124:127], v101, v75, v[124:127]
	v_fma_f32 v54, -v37, v57, v58
	v_fma_f32 v55, v37, v56, v59
	s_waitcnt lgkmcnt(9)
	v_fma_f32 v58, v36, v54, v12
	v_fma_f32 v59, v36, v55, v13
	v_mfma_f32_16x16x4_f32 v[128:131], v101, v82, v[128:131]
	v_mfma_f32_16x16x4_f32 v[132:135], v101, v83, v[132:135]
	v_fma_f32 v56, -v37, v55, v58
	v_fma_f32 v57, v37, v54, v59
	s_waitcnt lgkmcnt(8)
	v_fma_f32 v58, v36, v56, v14
	v_fma_f32 v59, v36, v57, v15
	v_mfma_f32_16x16x4_f32 v[136:139], v101, v90, v[136:139]
	v_mfma_f32_16x16x4_f32 v[140:143], v101, v91, v[140:143]
	v_fma_f32 v54, -v37, v57, v58
	v_fma_f32 v55, v37, v56, v59
	s_waitcnt lgkmcnt(7)
	v_fma_f32 v58, v36, v54, v16
	v_fma_f32 v59, v36, v55, v17
	v_mfma_f32_16x16x4_f32 v[112:115], v102, v68, v[112:115]
	v_mfma_f32_16x16x4_f32 v[116:119], v102, v69, v[116:119]
	v_fma_f32 v56, -v37, v55, v58
	v_fma_f32 v57, v37, v54, v59
	s_waitcnt lgkmcnt(6)
	v_fma_f32 v58, v36, v56, v18
	v_fma_f32 v59, v36, v57, v19
	v_mfma_f32_16x16x4_f32 v[120:123], v102, v76, v[120:123]
	v_mfma_f32_16x16x4_f32 v[124:127], v102, v77, v[124:127]
	v_fma_f32 v54, -v37, v57, v58
	v_fma_f32 v55, v37, v56, v59
	s_waitcnt lgkmcnt(5)
	v_fma_f32 v58, v36, v54, v20
	v_fma_f32 v59, v36, v55, v21
	v_mfma_f32_16x16x4_f32 v[128:131], v102, v84, v[128:131]
	v_mfma_f32_16x16x4_f32 v[132:135], v102, v85, v[132:135]
	v_fma_f32 v56, -v37, v55, v58
	v_fma_f32 v57, v37, v54, v59
	s_waitcnt lgkmcnt(4)
	v_fma_f32 v58, v36, v56, v22
	v_fma_f32 v59, v36, v57, v23
	v_mfma_f32_16x16x4_f32 v[136:139], v102, v92, v[136:139]
	v_mfma_f32_16x16x4_f32 v[140:143], v102, v93, v[140:143]
	v_fma_f32 v54, -v37, v57, v58
	v_fma_f32 v55, v37, v56, v59
	s_waitcnt lgkmcnt(3)
	v_fma_f32 v58, v36, v54, v24
	v_fma_f32 v59, v36, v55, v25
	v_mfma_f32_16x16x4_f32 v[112:115], v103, v70, v[112:115]
	v_mfma_f32_16x16x4_f32 v[116:119], v103, v71, v[116:119]
	v_fma_f32 v56, -v37, v55, v58
	v_fma_f32 v57, v37, v54, v59
	s_waitcnt lgkmcnt(2)
	v_fma_f32 v58, v36, v56, v26
	v_fma_f32 v59, v36, v57, v27
	v_mfma_f32_16x16x4_f32 v[120:123], v103, v78, v[120:123]
	v_mfma_f32_16x16x4_f32 v[124:127], v103, v79, v[124:127]
	v_fma_f32 v54, -v37, v57, v58
	v_fma_f32 v55, v37, v56, v59
	s_waitcnt lgkmcnt(1)
	v_fma_f32 v58, v36, v54, v28
	v_fma_f32 v59, v36, v55, v29
	v_mfma_f32_16x16x4_f32 v[128:131], v103, v86, v[128:131]
	v_mfma_f32_16x16x4_f32 v[132:135], v103, v87, v[132:135]
	v_fma_f32 v56, -v37, v55, v58
	v_fma_f32 v57, v37, v54, v59
	s_waitcnt lgkmcnt(0)
	v_fma_f32 v58, v36, v56, v30
	v_fma_f32 v59, v36, v57, v31
	v_mfma_f32_16x16x4_f32 v[136:139], v103, v94, v[136:139]
	v_mfma_f32_16x16x4_f32 v[140:143], v103, v95, v[140:143]
	v_fma_f32 v54, -v37, v57, v58
	v_fma_f32 v55, v37, v56, v59
	s_nop 15
	s_nop 15
	ds_write2_b32 v48, v112, v116 offset0:0 offset1:1
	ds_write2_b32 v49, v113, v117 offset0:0 offset1:1
	ds_write2_b32 v50, v114, v118 offset0:0 offset1:1
	ds_write2_b32 v51, v115, v119 offset0:0 offset1:1
	ds_write2_b32 v48, v120, v124 offset0:32 offset1:33
	ds_write2_b32 v49, v121, v125 offset0:32 offset1:33
	ds_write2_b32 v50, v122, v126 offset0:32 offset1:33
	ds_write2_b32 v51, v123, v127 offset0:32 offset1:33
	ds_write2_b32 v48, v128, v132 offset0:64 offset1:65
	ds_write2_b32 v49, v129, v133 offset0:64 offset1:65
	ds_write2_b32 v50, v130, v134 offset0:64 offset1:65
	ds_write2_b32 v51, v131, v135 offset0:64 offset1:65
	ds_write2_b32 v48, v136, v140 offset0:96 offset1:97
	ds_write2_b32 v49, v137, v141 offset0:96 offset1:97
	ds_write2_b32 v50, v138, v142 offset0:96 offset1:97
	ds_write2_b32 v51, v139, v143 offset0:96 offset1:97
	ds_read_b64 v[112:113], v52 offset:8192
	ds_read_b64 v[114:115], v52 offset:8704
	ds_read_b64 v[116:117], v52 offset:9216
	ds_read_b64 v[118:119], v52 offset:9728
	ds_read_b64 v[120:121], v52 offset:10240
	ds_read_b64 v[122:123], v52 offset:10752
	ds_read_b64 v[124:125], v52 offset:11264
	ds_read_b64 v[126:127], v52 offset:11776
	ds_read_b64 v[128:129], v52 offset:12288
	ds_read_b64 v[130:131], v52 offset:12800
	ds_read_b64 v[132:133], v52 offset:13312
	ds_read_b64 v[134:135], v52 offset:13824
	ds_read_b64 v[136:137], v52 offset:14336
	ds_read_b64 v[138:139], v52 offset:14848
	ds_read_b64 v[140:141], v52 offset:15360
	ds_read_b64 v[142:143], v52 offset:15872
	s_waitcnt vmcnt(1)
	s_waitcnt lgkmcnt(15)
; __device__ void phase_s5_pass1(CParams& p, int l, int item, char* smem) {
;     ...
;   for (int i = 0; i < 64; i++) {
;     int t = dir == 0 ? i : 63 - i;
;     float u[16];
; #pragma unroll
;     for (int k = 0; k < 4; k++) {
;       float4 uv = *(const float4*)(us + t * 16 + k * 4);
;       u[k * 4] = uv.x; u[k * 4 + 1] = uv.y; u[k * 4 + 2] = uv.z; u[k * 4 + 3] = uv.w;
;     }
;     f32x2 bu = {0.f, 0.f};
; #pragma unroll
;     for (int cc = 0; cc < 16; cc++) bu = __builtin_elementwise_fma(bb[cc], f32x2{u[cc], u[cc]}, bu);
;     float nr = A.x * hr - A.y * hi + bu[0];
;     float ni = A.x * hi + A.y * hr + bu[1];
;     hr = nr; hi = ni;
	v_fma_f32 v58, v36, v54, v112
	v_fma_f32 v59, v36, v55, v113
	v_mfma_f32_16x16x4_f32 v[0:3], v104, v64, 0
	v_mfma_f32_16x16x4_f32 v[4:7], v104, v65, 0
	v_fma_f32 v56, -v37, v55, v58
	v_fma_f32 v57, v37, v54, v59
	s_waitcnt lgkmcnt(14)
	v_fma_f32 v58, v36, v56, v114
	v_fma_f32 v59, v36, v57, v115
	v_mfma_f32_16x16x4_f32 v[8:11], v104, v72, 0
	v_mfma_f32_16x16x4_f32 v[12:15], v104, v73, 0
	v_fma_f32 v54, -v37, v57, v58
	v_fma_f32 v55, v37, v56, v59
	s_waitcnt lgkmcnt(13)
	v_fma_f32 v58, v36, v54, v116
	v_fma_f32 v59, v36, v55, v117
	v_mfma_f32_16x16x4_f32 v[16:19], v104, v80, 0
	v_mfma_f32_16x16x4_f32 v[20:23], v104, v81, 0
	v_fma_f32 v56, -v37, v55, v58
	v_fma_f32 v57, v37, v54, v59
	s_waitcnt lgkmcnt(12)
	v_fma_f32 v58, v36, v56, v118
	v_fma_f32 v59, v36, v57, v119
	v_mfma_f32_16x16x4_f32 v[24:27], v104, v88, 0
	v_mfma_f32_16x16x4_f32 v[28:31], v104, v89, 0
	v_fma_f32 v54, -v37, v57, v58
	v_fma_f32 v55, v37, v56, v59
	s_waitcnt lgkmcnt(11)
	v_fma_f32 v58, v36, v54, v120
	v_fma_f32 v59, v36, v55, v121
	v_mfma_f32_16x16x4_f32 v[0:3], v105, v66, v[0:3]
	v_mfma_f32_16x16x4_f32 v[4:7], v105, v67, v[4:7]
	v_fma_f32 v56, -v37, v55, v58
	v_fma_f32 v57, v37, v54, v59
	s_waitcnt lgkmcnt(10)
	v_fma_f32 v58, v36, v56, v122
	v_fma_f32 v59, v36, v57, v123
	v_mfma_f32_16x16x4_f32 v[8:11], v105, v74, v[8:11]
	v_mfma_f32_16x16x4_f32 v[12:15], v105, v75, v[12:15]
	v_fma_f32 v54, -v37, v57, v58
	v_fma_f32 v55, v37, v56, v59
	s_waitcnt lgkmcnt(9)
	v_fma_f32 v58, v36, v54, v124
	v_fma_f32 v59, v36, v55, v125
	v_mfma_f32_16x16x4_f32 v[16:19], v105, v82, v[16:19]
	v_mfma_f32_16x16x4_f32 v[20:23], v105, v83, v[20:23]
	v_fma_f32 v56, -v37, v55, v58
	v_fma_f32 v57, v37, v54, v59
	s_waitcnt lgkmcnt(8)
	v_fma_f32 v58, v36, v56, v126
	v_fma_f32 v59, v36, v57, v127
	v_mfma_f32_16x16x4_f32 v[24:27], v105, v90, v[24:27]
	v_mfma_f32_16x16x4_f32 v[28:31], v105, v91, v[28:31]
	v_fma_f32 v54, -v37, v57, v58
	v_fma_f32 v55, v37, v56, v59
	s_waitcnt lgkmcnt(7)
	v_fma_f32 v58, v36, v54, v128
	v_fma_f32 v59, v36, v55, v129
	v_mfma_f32_16x16x4_f32 v[0:3], v106, v68, v[0:3]
	v_mfma_f32_16x16x4_f32 v[4:7], v106, v69, v[4:7]
	v_fma_f32 v56, -v37, v55, v58
	v_fma_f32 v57, v37, v54, v59
	s_waitcnt lgkmcnt(6)
	v_fma_f32 v58, v36, v56, v130
	v_fma_f32 v59, v36, v57, v131
	v_mfma_f32_16x16x4_f32 v[8:11], v106, v76, v[8:11]
	v_mfma_f32_16x16x4_f32 v[12:15], v106, v77, v[12:15]
	v_fma_f32 v54, -v37, v57, v58
	v_fma_f32 v55, v37, v56, v59
	s_waitcnt lgkmcnt(5)
	v_fma_f32 v58, v36, v54, v132
	v_fma_f32 v59, v36, v55, v133
	v_mfma_f32_16x16x4_f32 v[16:19], v106, v84, v[16:19]
	v_mfma_f32_16x16x4_f32 v[20:23], v106, v85, v[20:23]
	v_fma_f32 v56, -v37, v55, v58
	v_fma_f32 v57, v37, v54, v59
	s_waitcnt lgkmcnt(4)
	v_fma_f32 v58, v36, v56, v134
	v_fma_f32 v59, v36, v57, v135
	v_mfma_f32_16x16x4_f32 v[24:27], v106, v92, v[24:27]
	v_mfma_f32_16x16x4_f32 v[28:31], v106, v93, v[28:31]
	v_fma_f32 v54, -v37, v57, v58
	v_fma_f32 v55, v37, v56, v59
	s_waitcnt lgkmcnt(3)
	v_fma_f32 v58, v36, v54, v136
	v_fma_f32 v59, v36, v55, v137
	v_mfma_f32_16x16x4_f32 v[0:3], v107, v70, v[0:3]
	v_mfma_f32_16x16x4_f32 v[4:7], v107, v71, v[4:7]
	v_fma_f32 v56, -v37, v55, v58
	v_fma_f32 v57, v37, v54, v59
	s_waitcnt lgkmcnt(2)
	v_fma_f32 v58, v36, v56, v138
	v_fma_f32 v59, v36, v57, v139
	v_mfma_f32_16x16x4_f32 v[8:11], v107, v78, v[8:11]
	v_mfma_f32_16x16x4_f32 v[12:15], v107, v79, v[12:15]
	v_fma_f32 v54, -v37, v57, v58
	v_fma_f32 v55, v37, v56, v59
	s_waitcnt lgkmcnt(1)
	v_fma_f32 v58, v36, v54, v140
	v_fma_f32 v59, v36, v55, v141
	v_mfma_f32_16x16x4_f32 v[16:19], v107, v86, v[16:19]
	v_mfma_f32_16x16x4_f32 v[20:23], v107, v87, v[20:23]
	v_fma_f32 v56, -v37, v55, v58
	v_fma_f32 v57, v37, v54, v59
	s_waitcnt lgkmcnt(0)
	v_fma_f32 v58, v36, v56, v142
	v_fma_f32 v59, v36, v57, v143
	v_mfma_f32_16x16x4_f32 v[24:27], v107, v94, v[24:27]
	v_mfma_f32_16x16x4_f32 v[28:31], v107, v95, v[28:31]
	v_fma_f32 v54, -v37, v57, v58
	v_fma_f32 v55, v37, v56, v59
	s_nop 15
	s_nop 15
	ds_write2_b32 v44, v0, v4 offset0:0 offset1:1
	ds_write2_b32 v45, v1, v5 offset0:0 offset1:1
	ds_write2_b32 v46, v2, v6 offset0:0 offset1:1
	ds_write2_b32 v47, v3, v7 offset0:0 offset1:1
	ds_write2_b32 v44, v8, v12 offset0:32 offset1:33
	ds_write2_b32 v45, v9, v13 offset0:32 offset1:33
	ds_write2_b32 v46, v10, v14 offset0:32 offset1:33
	ds_write2_b32 v47, v11, v15 offset0:32 offset1:33
	ds_write2_b32 v44, v16, v20 offset0:64 offset1:65
	ds_write2_b32 v45, v17, v21 offset0:64 offset1:65
	ds_write2_b32 v46, v18, v22 offset0:64 offset1:65
	ds_write2_b32 v47, v19, v23 offset0:64 offset1:65
	ds_write2_b32 v44, v24, v28 offset0:96 offset1:97
	ds_write2_b32 v45, v25, v29 offset0:96 offset1:97
	ds_write2_b32 v46, v26, v30 offset0:96 offset1:97
	ds_write2_b32 v47, v27, v31 offset0:96 offset1:97
	ds_read_b64 v[0:1], v52 offset:0
	ds_read_b64 v[2:3], v52 offset:512
	ds_read_b64 v[4:5], v52 offset:1024
	ds_read_b64 v[6:7], v52 offset:1536
	ds_read_b64 v[8:9], v52 offset:2048
	ds_read_b64 v[10:11], v52 offset:2560
	ds_read_b64 v[12:13], v52 offset:3072
	ds_read_b64 v[14:15], v52 offset:3584
	ds_read_b64 v[16:17], v52 offset:4096
	ds_read_b64 v[18:19], v52 offset:4608
	ds_read_b64 v[20:21], v52 offset:5120
	ds_read_b64 v[22:23], v52 offset:5632
	ds_read_b64 v[24:25], v52 offset:6144
	ds_read_b64 v[26:27], v52 offset:6656
	ds_read_b64 v[28:29], v52 offset:7168
	ds_read_b64 v[30:31], v52 offset:7680
	s_waitcnt vmcnt(0)
	s_waitcnt lgkmcnt(15)
	v_fma_f32 v58, v36, v54, v0
	v_fma_f32 v59, v36, v55, v1
	v_mfma_f32_16x16x4_f32 v[112:115], v108, v64, 0
	v_mfma_f32_16x16x4_f32 v[116:119], v108, v65, 0
	v_fma_f32 v56, -v37, v55, v58
	v_fma_f32 v57, v37, v54, v59
	s_waitcnt lgkmcnt(14)
; __device__ void phase_s5_pass1(CParams& p, int l, int item, char* smem) {
;     ...
;   for (int i = 0; i < 64; i++) {
;     int t = dir == 0 ? i : 63 - i;
;     float u[16];
; #pragma unroll
;     for (int k = 0; k < 4; k++) {
;       float4 uv = *(const float4*)(us + t * 16 + k * 4);
;       u[k * 4] = uv.x; u[k * 4 + 1] = uv.y; u[k * 4 + 2] = uv.z; u[k * 4 + 3] = uv.w;
;     }
;     f32x2 bu = {0.f, 0.f};
; #pragma unroll
;     for (int cc = 0; cc < 16; cc++) bu = __builtin_elementwise_fma(bb[cc], f32x2{u[cc], u[cc]}, bu);
;     float nr = A.x * hr - A.y * hi + bu[0];
;     float ni = A.x * hi + A.y * hr + bu[1];
;     hr = nr; hi = ni;
	v_fma_f32 v58, v36, v56, v2
	v_fma_f32 v59, v36, v57, v3
	v_mfma_f32_16x16x4_f32 v[120:123], v108, v72, 0
	v_mfma_f32_16x16x4_f32 v[124:127], v108, v73, 0
	v_fma_f32 v54, -v37, v57, v58
	v_fma_f32 v55, v37, v56, v59
	s_waitcnt lgkmcnt(13)
	v_fma_f32 v58, v36, v54, v4
	v_fma_f32 v59, v36, v55, v5
	v_mfma_f32_16x16x4_f32 v[128:131], v108, v80, 0
	v_mfma_f32_16x16x4_f32 v[132:135], v108, v81, 0
	v_fma_f32 v56, -v37, v55, v58
	v_fma_f32 v57, v37, v54, v59
	s_waitcnt lgkmcnt(12)
	v_fma_f32 v58, v36, v56, v6
	v_fma_f32 v59, v36, v57, v7
	v_mfma_f32_16x16x4_f32 v[136:139], v108, v88, 0
	v_mfma_f32_16x16x4_f32 v[140:143], v108, v89, 0
	v_fma_f32 v54, -v37, v57, v58
	v_fma_f32 v55, v37, v56, v59
	s_waitcnt lgkmcnt(11)
	v_fma_f32 v58, v36, v54, v8
	v_fma_f32 v59, v36, v55, v9
	v_mfma_f32_16x16x4_f32 v[112:115], v109, v66, v[112:115]
	v_mfma_f32_16x16x4_f32 v[116:119], v109, v67, v[116:119]
	v_fma_f32 v56, -v37, v55, v58
	v_fma_f32 v57, v37, v54, v59
	s_waitcnt lgkmcnt(10)
	v_fma_f32 v58, v36, v56, v10
	v_fma_f32 v59, v36, v57, v11
	v_mfma_f32_16x16x4_f32 v[120:123], v109, v74, v[120:123]
	v_mfma_f32_16x16x4_f32 v[124:127], v109, v75, v[124:127]
	v_fma_f32 v54, -v37, v57, v58
	v_fma_f32 v55, v37, v56, v59
	s_waitcnt lgkmcnt(9)
	v_fma_f32 v58, v36, v54, v12
	v_fma_f32 v59, v36, v55, v13
	v_mfma_f32_16x16x4_f32 v[128:131], v109, v82, v[128:131]
	v_mfma_f32_16x16x4_f32 v[132:135], v109, v83, v[132:135]
	v_fma_f32 v56, -v37, v55, v58
	v_fma_f32 v57, v37, v54, v59
	s_waitcnt lgkmcnt(8)
	v_fma_f32 v58, v36, v56, v14
	v_fma_f32 v59, v36, v57, v15
	v_mfma_f32_16x16x4_f32 v[136:139], v109, v90, v[136:139]
	v_mfma_f32_16x16x4_f32 v[140:143], v109, v91, v[140:143]
	v_fma_f32 v54, -v37, v57, v58
	v_fma_f32 v55, v37, v56, v59
	s_waitcnt lgkmcnt(7)
	v_fma_f32 v58, v36, v54, v16
	v_fma_f32 v59, v36, v55, v17
	v_mfma_f32_16x16x4_f32 v[112:115], v110, v68, v[112:115]
	v_mfma_f32_16x16x4_f32 v[116:119], v110, v69, v[116:119]
	v_fma_f32 v56, -v37, v55, v58
	v_fma_f32 v57, v37, v54, v59
	s_waitcnt lgkmcnt(6)
	v_fma_f32 v58, v36, v56, v18
	v_fma_f32 v59, v36, v57, v19
	v_mfma_f32_16x16x4_f32 v[120:123], v110, v76, v[120:123]
	v_mfma_f32_16x16x4_f32 v[124:127], v110, v77, v[124:127]
	v_fma_f32 v54, -v37, v57, v58
	v_fma_f32 v55, v37, v56, v59
	s_waitcnt lgkmcnt(5)
	v_fma_f32 v58, v36, v54, v20
	v_fma_f32 v59, v36, v55, v21
	v_mfma_f32_16x16x4_f32 v[128:131], v110, v84, v[128:131]
	v_mfma_f32_16x16x4_f32 v[132:135], v110, v85, v[132:135]
	v_fma_f32 v56, -v37, v55, v58
	v_fma_f32 v57, v37, v54, v59
	s_waitcnt lgkmcnt(4)
	v_fma_f32 v58, v36, v56, v22
	v_fma_f32 v59, v36, v57, v23
	v_mfma_f32_16x16x4_f32 v[136:139], v110, v92, v[136:139]
	v_mfma_f32_16x16x4_f32 v[140:143], v110, v93, v[140:143]
	v_fma_f32 v54, -v37, v57, v58
	v_fma_f32 v55, v37, v56, v59
	s_waitcnt lgkmcnt(3)
	v_fma_f32 v58, v36, v54, v24
	v_fma_f32 v59, v36, v55, v25
	v_mfma_f32_16x16x4_f32 v[112:115], v111, v70, v[112:115]
	v_mfma_f32_16x16x4_f32 v[116:119], v111, v71, v[116:119]
	v_fma_f32 v56, -v37, v55, v58
	v_fma_f32 v57, v37, v54, v59
	s_waitcnt lgkmcnt(2)
	v_fma_f32 v58, v36, v56, v26
	v_fma_f32 v59, v36, v57, v27
	v_mfma_f32_16x16x4_f32 v[120:123], v111, v78, v[120:123]
	v_mfma_f32_16x16x4_f32 v[124:127], v111, v79, v[124:127]
	v_fma_f32 v54, -v37, v57, v58
	v_fma_f32 v55, v37, v56, v59
	s_waitcnt lgkmcnt(1)
	v_fma_f32 v58, v36, v54, v28
	v_fma_f32 v59, v36, v55, v29
	v_mfma_f32_16x16x4_f32 v[128:131], v111, v86, v[128:131]
	v_mfma_f32_16x16x4_f32 v[132:135], v111, v87, v[132:135]
	v_fma_f32 v56, -v37, v55, v58
	v_fma_f32 v57, v37, v54, v59
	s_waitcnt lgkmcnt(0)
; __device__ void phase_s5_pass1(CParams& p, int l, int item, char* smem) {
;     ...
;   for (int i = 0; i < 64; i++) {
;     int t = dir == 0 ? i : 63 - i;
;     float u[16];
; #pragma unroll
;     for (int k = 0; k < 4; k++) {
;       float4 uv = *(const float4*)(us + t * 16 + k * 4);
;       u[k * 4] = uv.x; u[k * 4 + 1] = uv.y; u[k * 4 + 2] = uv.z; u[k * 4 + 3] = uv.w;
;     }
;     f32x2 bu = {0.f, 0.f};
; #pragma unroll
;     for (int cc = 0; cc < 16; cc++) bu = __builtin_elementwise_fma(bb[cc], f32x2{u[cc], u[cc]}, bu);
;     float nr = A.x * hr - A.y * hi + bu[0];
;     float ni = A.x * hi + A.y * hr + bu[1];
;     hr = nr; hi = ni;
;   }
;   p.E[(((size_t)q * 2 + dir) * 16 + g) * 64 + lane] = make_float2(hr, hi);
	v_fma_f32 v58, v36, v56, v30
	v_fma_f32 v59, v36, v57, v31
	v_mfma_f32_16x16x4_f32 v[136:139], v111, v94, v[136:139]
	v_mfma_f32_16x16x4_f32 v[140:143], v111, v95, v[140:143]
	v_fma_f32 v54, -v37, v57, v58
	v_fma_f32 v55, v37, v56, v59
	s_nop 15
	s_nop 15
	ds_write2_b32 v48, v112, v116 offset0:0 offset1:1
	ds_write2_b32 v49, v113, v117 offset0:0 offset1:1
	ds_write2_b32 v50, v114, v118 offset0:0 offset1:1
	ds_write2_b32 v51, v115, v119 offset0:0 offset1:1
	ds_write2_b32 v48, v120, v124 offset0:32 offset1:33
	ds_write2_b32 v49, v121, v125 offset0:32 offset1:33
	ds_write2_b32 v50, v122, v126 offset0:32 offset1:33
	ds_write2_b32 v51, v123, v127 offset0:32 offset1:33
	ds_write2_b32 v48, v128, v132 offset0:64 offset1:65
	ds_write2_b32 v49, v129, v133 offset0:64 offset1:65
	ds_write2_b32 v50, v130, v134 offset0:64 offset1:65
	ds_write2_b32 v51, v131, v135 offset0:64 offset1:65
	ds_write2_b32 v48, v136, v140 offset0:96 offset1:97
	ds_write2_b32 v49, v137, v141 offset0:96 offset1:97
	ds_write2_b32 v50, v138, v142 offset0:96 offset1:97
	ds_write2_b32 v51, v139, v143 offset0:96 offset1:97
	ds_read_b64 v[112:113], v52 offset:8192
	ds_read_b64 v[114:115], v52 offset:8704
	ds_read_b64 v[116:117], v52 offset:9216
	ds_read_b64 v[118:119], v52 offset:9728
	ds_read_b64 v[120:121], v52 offset:10240
	ds_read_b64 v[122:123], v52 offset:10752
	ds_read_b64 v[124:125], v52 offset:11264
	ds_read_b64 v[126:127], v52 offset:11776
	ds_read_b64 v[128:129], v52 offset:12288
	ds_read_b64 v[130:131], v52 offset:12800
	ds_read_b64 v[132:133], v52 offset:13312
	ds_read_b64 v[134:135], v52 offset:13824
	ds_read_b64 v[136:137], v52 offset:14336
	ds_read_b64 v[138:139], v52 offset:14848
	ds_read_b64 v[140:141], v52 offset:15360
	ds_read_b64 v[142:143], v52 offset:15872
	s_waitcnt lgkmcnt(15)
	v_fma_f32 v58, v36, v54, v112
	v_fma_f32 v59, v36, v55, v113
	v_fma_f32 v56, -v37, v55, v58
	v_fma_f32 v57, v37, v54, v59
	s_waitcnt lgkmcnt(14)
	v_fma_f32 v58, v36, v56, v114
	v_fma_f32 v59, v36, v57, v115
	v_fma_f32 v54, -v37, v57, v58
	v_fma_f32 v55, v37, v56, v59
	s_waitcnt lgkmcnt(13)
	v_fma_f32 v58, v36, v54, v116
	v_fma_f32 v59, v36, v55, v117
	v_fma_f32 v56, -v37, v55, v58
	v_fma_f32 v57, v37, v54, v59
	s_waitcnt lgkmcnt(12)
	v_fma_f32 v58, v36, v56, v118
	v_fma_f32 v59, v36, v57, v119
	v_fma_f32 v54, -v37, v57, v58
	v_fma_f32 v55, v37, v56, v59
	s_waitcnt lgkmcnt(11)
	v_fma_f32 v58, v36, v54, v120
	v_fma_f32 v59, v36, v55, v121
	v_fma_f32 v56, -v37, v55, v58
	v_fma_f32 v57, v37, v54, v59
	s_waitcnt lgkmcnt(10)
	v_fma_f32 v58, v36, v56, v122
	v_fma_f32 v59, v36, v57, v123
	v_fma_f32 v54, -v37, v57, v58
	v_fma_f32 v55, v37, v56, v59
	s_waitcnt lgkmcnt(9)
	v_fma_f32 v58, v36, v54, v124
	v_fma_f32 v59, v36, v55, v125
	v_fma_f32 v56, -v37, v55, v58
	v_fma_f32 v57, v37, v54, v59
	s_waitcnt lgkmcnt(8)
	v_fma_f32 v58, v36, v56, v126
	v_fma_f32 v59, v36, v57, v127
	v_fma_f32 v54, -v37, v57, v58
	v_fma_f32 v55, v37, v56, v59
	s_waitcnt lgkmcnt(7)
	v_fma_f32 v58, v36, v54, v128
	v_fma_f32 v59, v36, v55, v129
	v_fma_f32 v56, -v37, v55, v58
	v_fma_f32 v57, v37, v54, v59
	s_waitcnt lgkmcnt(6)
	v_fma_f32 v58, v36, v56, v130
	v_fma_f32 v59, v36, v57, v131
	v_fma_f32 v54, -v37, v57, v58
	v_fma_f32 v55, v37, v56, v59
	s_waitcnt lgkmcnt(5)
	v_fma_f32 v58, v36, v54, v132
	v_fma_f32 v59, v36, v55, v133
	v_fma_f32 v56, -v37, v55, v58
	v_fma_f32 v57, v37, v54, v59
	s_waitcnt lgkmcnt(4)
	v_fma_f32 v58, v36, v56, v134
	v_fma_f32 v59, v36, v57, v135
	v_fma_f32 v54, -v37, v57, v58
	v_fma_f32 v55, v37, v56, v59
	s_waitcnt lgkmcnt(3)
	v_fma_f32 v58, v36, v54, v136
	v_fma_f32 v59, v36, v55, v137
	v_fma_f32 v56, -v37, v55, v58
	v_fma_f32 v57, v37, v54, v59
	s_waitcnt lgkmcnt(2)
	v_fma_f32 v58, v36, v56, v138
	v_fma_f32 v59, v36, v57, v139
	v_fma_f32 v54, -v37, v57, v58
	v_fma_f32 v55, v37, v56, v59
	s_waitcnt lgkmcnt(1)
	v_fma_f32 v58, v36, v54, v140
	v_fma_f32 v59, v36, v55, v141
	v_fma_f32 v56, -v37, v55, v58
	v_fma_f32 v57, v37, v54, v59
	s_waitcnt lgkmcnt(0)
	v_fma_f32 v58, v36, v56, v142
	v_fma_f32 v59, v36, v57, v143
	v_fma_f32 v54, -v37, v57, v58
	v_fma_f32 v55, v37, v56, v59
	v_lshlrev_b32_e32 v38, 3, v32
	global_store_dwordx2 v38, v[54:55], s[18:19]
	s_waitcnt lgkmcnt(0)
	s_barrier
	s_mov_b64 s[26:27], 0
	s_movk_i32 s0, 0x4000

; __device__ void phase_s5_pass2(CParams& p, int l, int item, char* smem) {
;     ...
;   int q = item >> 2, gq = item & 3;
;   int g = gq * 4 + wid;
;   float* us = (float*)smem + wid * 1024;
;   bf16_t* hs = (bf16_t*)(smem + 16384) + wid * (16 * 136);
;   int tok0 = q * 64;
;   __syncthreads();
;   {
;     const float* src = p.zs5 + (size_t)(tok0 + lane) * 256 + g * 16;
; #pragma unroll
;     for (int i = 0; i < 4; i++) *(float4*)(us + lane * 16 + i * 4) = *(const float4*)(src + i * 4);
;   }
;   __syncthreads();
;   f32x4 acc[4];
; #pragma unroll
;   for (int s = 0; s < 4; s++) acc[s] = f32x4{0.f, 0.f, 0.f, 0.f};
;   const int l15 = lane & 15, lq = lane >> 4;
; #pragma unroll
;   for (int dir = 0; dir < 2; dir++) {
;     int pidx = ((l * 2 + dir) * 16 + g) * 64 + lane;
;     float2 A = p.Apar[pidx];
;     f32x2 bb[16];
; #pragma unroll
;     for (int cc = 0; cc < 16; cc++) {
;       float2 b = p.Bbar[(size_t)pidx * 16 + cc];
;       bb[cc] = f32x2{b.x, b.y};
;     }
;     bf16x8 cf[4];
; #pragma unroll
;     for (int ks = 0; ks < 4; ks++) {
;       int k = ks * 32 + lq * 8;
;       bool im = k >= 64;
;       const float* src = (im ? p.c_im : p.c_re) + ((((size_t)(l * 2 + dir) * 16 + g) * 16 + l15) * 64) + (k & 63);
;       float4 v0 = *(const float4*)src, v1 = *(const float4*)(src + 4);
;       float sgn = im ? -1.f : 1.f;
;       cf[ks][0] = (short)f2bf(sgn * v0.x); cf[ks][1] = (short)f2bf(sgn * v0.y);
;       cf[ks][2] = (short)f2bf(sgn * v0.z); cf[ks][3] = (short)f2bf(sgn * v0.w);
;       cf[ks][4] = (short)f2bf(sgn * v1.x); cf[ks][5] = (short)f2bf(sgn * v1.y);
;       cf[ks][6] = (short)f2bf(sgn * v1.z); cf[ks][7] = (short)f2bf(sgn * v1.w);
;     }
;     float2 h0 = p.Hin[(((size_t)q * 2 + dir) * 16 + g) * 64 + lane];
;     float hr = h0.x, hi = h0.y;
.LBB0_701:
	s_load_dwordx2 s[6:7], s[44:45], 0x190
	s_load_dwordx2 s[8:9], s[44:45], 0x1b8
	v_readlane_b32 s12, v224, 26
	v_readfirstlane_b32 s4, v147
	v_and_b32_e32 v32, 63, v147
	s_lshr_b32 s1, s42, 2
	s_and_b32 s2, s42, 3
	s_lshl_b32 s2, s2, 2
	s_lshr_b32 s4, s4, 6
	s_add_u32 s2, s2, s4
	s_mov_b32 s99, 0x0
	s_cmp_eq_u32 s4, 1
	s_cselect_b32 s99, 0x3400, s99
	s_cmp_eq_u32 s4, 2
	s_cselect_b32 s99, 0x6800, s99
	s_cmp_eq_u32 s4, 3
	s_cselect_b32 s99, 0xa400, s99
	v_and_b32_e32 v33, 15, v32
	v_lshrrev_b32_e32 v34, 4, v32
	v_lshlrev_b32_e32 v40, 7, v33
	v_lshl_add_u32 v40, v34, 5, v40
	v_add_u32_e32 v41, 0x1000, v40
	v_lshlrev_b32_e32 v38, 11, v34
	v_lshl_add_u32 v38, v33, 3, v38
	v_add_u32_e32 v38, s99, v38
	v_add_u32_e32 v44, 0x0, v38
	v_add_u32_e32 v45, 0x200, v38
	v_add_u32_e32 v46, 0x400, v38
	v_add_u32_e32 v47, 0x600, v38
	v_lshlrev_b32_e32 v52, 3, v32
	v_add_u32_e32 v52, s99, v52
	v_lshlrev_b32_e32 v60, 1, v32
	v_add_u32_e32 v60, s99, v60
	v_add_u32_e32 v60, 0x2000, v60
	v_mul_u32_u24_e32 v61, 0x110, v33
	v_lshl_add_u32 v61, v34, 4, v61
	v_add_u32_e32 v61, s99, v61
	v_add_u32_e32 v61, 0x2000, v61
	v_lshlrev_b32_e32 v49, 8, v33
	v_lshl_add_u32 v49, v34, 5, v49
	v_lshlrev_b32_e32 v63, 12, v34
	v_lshl_add_u32 v63, v33, 2, v63
	v_lshlrev_b32_e32 v48, 11, v34
	v_lshl_add_u32 v48, v33, 1, v48
	v_mov_b32_e32 v148, 0
	v_mov_b32_e32 v149, 0
	v_mov_b32_e32 v150, 0
	v_mov_b32_e32 v151, 0
	v_mov_b32_e32 v152, 0
	v_mov_b32_e32 v153, 0
	v_mov_b32_e32 v154, 0
	v_mov_b32_e32 v155, 0
	v_mov_b32_e32 v156, 0
	v_mov_b32_e32 v157, 0
	v_mov_b32_e32 v158, 0
	v_mov_b32_e32 v159, 0
	v_mov_b32_e32 v160, 0
	v_mov_b32_e32 v161, 0
	v_mov_b32_e32 v162, 0
	v_mov_b32_e32 v163, 0
	s_waitcnt lgkmcnt(0)
	s_lshl_b32 s20, s1, 16
	s_lshl_b32 s32, s2, 6
	s_add_u32 s20, s20, s32
	s_add_u32 s6, s6, s20
	s_addc_u32 s7, s7, 0
	s_lshr_b32 s20, s20, 1
	s_add_u32 s8, s8, s20
	s_addc_u32 s9, s9, 0
	s_barrier
	s_lshl_b32 s20, s12, 1
	s_add_u32 s20, s20, 0
	s_lshl_b32 s20, s20, 4
	s_add_u32 s20, s20, s2
	s_lshl_b32 s19, s20, 6
	s_load_dwordx2 s[22:23], s[44:45], 0x168
	s_load_dwordx2 s[24:25], s[44:45], 0x170
	s_load_dwordx2 s[26:27], s[44:45], 0x68
	s_load_dwordx2 s[34:35], s[44:45], 0x70
	s_load_dwordx2 s[40:41], s[44:45], 0x180
	s_waitcnt lgkmcnt(0)
	s_lshl_b32 s20, s19, 3
	s_add_u32 s22, s22, s20
	s_addc_u32 s23, s23, 0
	s_lshl_b32 s20, s19, 7
	s_add_u32 s24, s24, s20
	s_addc_u32 s25, s25, 0
	s_lshl_b32 s20, s19, 6
	s_add_u32 s26, s26, s20
	s_addc_u32 s27, s27, 0
	s_add_u32 s34, s34, s20
	s_addc_u32 s35, s35, 0
	s_lshl_b32 s20, s1, 1
	s_add_u32 s20, s20, 0
	s_lshl_b32 s20, s20, 4
	s_add_u32 s20, s20, s2
	s_lshl_b32 s20, s20, 9
	s_add_u32 s40, s40, s20
	s_addc_u32 s41, s41, 0
	v_lshlrev_b32_e32 v38, 3, v32
	global_load_dwordx2 v[36:37], v38, s[22:23]
	global_load_dwordx2 v[54:55], v38, s[40:41]
	global_load_dwordx4 v[64:67], v40, s[24:25] offset:0
	global_load_dwordx4 v[68:71], v40, s[24:25] offset:16
	global_load_dwordx4 v[72:75], v40, s[24:25] offset:2048
	global_load_dwordx4 v[76:79], v40, s[24:25] offset:2064
	global_load_dwordx4 v[80:83], v41, s[24:25] offset:0
	global_load_dwordx4 v[84:87], v41, s[24:25] offset:16
	global_load_dwordx4 v[88:91], v41, s[24:25] offset:2048
	global_load_dwordx4 v[92:95], v41, s[24:25] offset:2064
	global_load_dwordx4 v[112:115], v49, s[26:27] offset:0
	global_load_dwordx4 v[116:119], v49, s[26:27] offset:16
	global_load_dwordx4 v[120:123], v49, s[26:27] offset:128
	global_load_dwordx4 v[124:127], v49, s[26:27] offset:144
	global_load_dwordx4 v[128:131], v49, s[34:35] offset:0
	global_load_dwordx4 v[132:135], v49, s[34:35] offset:16
	global_load_dwordx4 v[136:139], v49, s[34:35] offset:128
	global_load_dwordx4 v[140:143], v49, s[34:35] offset:144
	v_lshlrev_b32_e32 v42, 10, v33
	v_lshl_add_u32 v42, v34, 4, v42
	s_mov_b32 s98, 0x4000
	global_load_dwordx4 v[96:99], v42, s[6:7]
	v_add_u32_e32 v42, s98, v42
	global_load_dwordx4 v[100:103], v42, s[6:7]
	v_add_u32_e32 v42, s98, v42
	global_load_dwordx4 v[104:107], v42, s[6:7]
	v_add_u32_e32 v42, s98, v42
	global_load_dwordx4 v[108:111], v42, s[6:7]
	s_waitcnt vmcnt(4)
	v_cvt_pk_bf16_f32 v168, v112, v113
	v_cvt_pk_bf16_f32 v169, v114, v115
	v_cvt_pk_bf16_f32 v170, v116, v117
	v_cvt_pk_bf16_f32 v171, v118, v119
	v_cvt_pk_bf16_f32 v172, v120, v121
	v_cvt_pk_bf16_f32 v173, v122, v123
	v_cvt_pk_bf16_f32 v174, v124, v125
	v_cvt_pk_bf16_f32 v175, v126, v127
	v_cvt_pk_bf16_f32 v176, v128, v129
	v_xor_b32_e32 v176, 0x80008000, v176
	v_cvt_pk_bf16_f32 v177, v130, v131
	v_xor_b32_e32 v177, 0x80008000, v177
	v_cvt_pk_bf16_f32 v178, v132, v133
	v_xor_b32_e32 v178, 0x80008000, v178
	v_cvt_pk_bf16_f32 v179, v134, v135
	v_xor_b32_e32 v179, 0x80008000, v179
	v_cvt_pk_bf16_f32 v180, v136, v137
	v_xor_b32_e32 v180, 0x80008000, v180
	v_cvt_pk_bf16_f32 v181, v138, v139
	v_xor_b32_e32 v181, 0x80008000, v181
	v_cvt_pk_bf16_f32 v182, v140, v141
	v_xor_b32_e32 v182, 0x80008000, v182
	v_cvt_pk_bf16_f32 v183, v142, v143
	v_xor_b32_e32 v183, 0x80008000, v183
	s_waitcnt vmcnt(3)
; __device__ void phase_s5_pass2(CParams& p, int l, int item, char* smem) {
;     ...
;     for (int s = 0; s < 4; s++) {
;       const int sb = dir == 0 ? s : 3 - s;
;       for (int i = 0; i < 16; i++) {
;         int tl = dir == 0 ? i : 15 - i;
;         int t = sb * 16 + tl;
;         float u[16];
; #pragma unroll
;         for (int k = 0; k < 4; k++) {
;           float4 uv = *(const float4*)(us + t * 16 + k * 4);
;           u[k * 4] = uv.x; u[k * 4 + 1] = uv.y; u[k * 4 + 2] = uv.z; u[k * 4 + 3] = uv.w;
;         }
;         f32x2 bu = {0.f, 0.f};
; #pragma unroll
;         for (int cc = 0; cc < 16; cc++) bu = __builtin_elementwise_fma(bb[cc], f32x2{u[cc], u[cc]}, bu);
;         float nr = A.x * hr - A.y * hi + bu[0];
;         float ni = A.x * hi + A.y * hr + bu[1];
;         hr = nr; hi = ni;
;         hs[tl * 136 + lane] = f2bf(hr);
;         hs[tl * 136 + 64 + lane] = f2bf(hi);
;       }
	v_mfma_f32_16x16x4_f32 v[0:3], v96, v64, 0
	v_mfma_f32_16x16x4_f32 v[4:7], v96, v65, 0
	v_mfma_f32_16x16x4_f32 v[8:11], v96, v72, 0
	v_mfma_f32_16x16x4_f32 v[12:15], v96, v73, 0
	v_mfma_f32_16x16x4_f32 v[16:19], v96, v80, 0
	v_mfma_f32_16x16x4_f32 v[20:23], v96, v81, 0
	v_mfma_f32_16x16x4_f32 v[24:27], v96, v88, 0
	v_mfma_f32_16x16x4_f32 v[28:31], v96, v89, 0
	v_mfma_f32_16x16x4_f32 v[0:3], v97, v66, v[0:3]
	v_mfma_f32_16x16x4_f32 v[4:7], v97, v67, v[4:7]
	v_mfma_f32_16x16x4_f32 v[8:11], v97, v74, v[8:11]
	v_mfma_f32_16x16x4_f32 v[12:15], v97, v75, v[12:15]
	v_mfma_f32_16x16x4_f32 v[16:19], v97, v82, v[16:19]
	v_mfma_f32_16x16x4_f32 v[20:23], v97, v83, v[20:23]
	v_mfma_f32_16x16x4_f32 v[24:27], v97, v90, v[24:27]
	v_mfma_f32_16x16x4_f32 v[28:31], v97, v91, v[28:31]
	v_mfma_f32_16x16x4_f32 v[0:3], v98, v68, v[0:3]
	v_mfma_f32_16x16x4_f32 v[4:7], v98, v69, v[4:7]
	v_mfma_f32_16x16x4_f32 v[8:11], v98, v76, v[8:11]
	v_mfma_f32_16x16x4_f32 v[12:15], v98, v77, v[12:15]
	v_mfma_f32_16x16x4_f32 v[16:19], v98, v84, v[16:19]
	v_mfma_f32_16x16x4_f32 v[20:23], v98, v85, v[20:23]
	v_mfma_f32_16x16x4_f32 v[24:27], v98, v92, v[24:27]
	v_mfma_f32_16x16x4_f32 v[28:31], v98, v93, v[28:31]
	v_mfma_f32_16x16x4_f32 v[0:3], v99, v70, v[0:3]
	v_mfma_f32_16x16x4_f32 v[4:7], v99, v71, v[4:7]
	v_mfma_f32_16x16x4_f32 v[8:11], v99, v78, v[8:11]
	v_mfma_f32_16x16x4_f32 v[12:15], v99, v79, v[12:15]
	v_mfma_f32_16x16x4_f32 v[16:19], v99, v86, v[16:19]
	v_mfma_f32_16x16x4_f32 v[20:23], v99, v87, v[20:23]
	v_mfma_f32_16x16x4_f32 v[24:27], v99, v94, v[24:27]
	v_mfma_f32_16x16x4_f32 v[28:31], v99, v95, v[28:31]
	s_nop 15
	s_nop 15
	ds_write2_b32 v44, v0, v4 offset0:0 offset1:1
	ds_write2_b32 v45, v1, v5 offset0:0 offset1:1
	ds_write2_b32 v46, v2, v6 offset0:0 offset1:1
	ds_write2_b32 v47, v3, v7 offset0:0 offset1:1
	ds_write2_b32 v44, v8, v12 offset0:32 offset1:33
	ds_write2_b32 v45, v9, v13 offset0:32 offset1:33
	ds_write2_b32 v46, v10, v14 offset0:32 offset1:33
	ds_write2_b32 v47, v11, v15 offset0:32 offset1:33
	ds_write2_b32 v44, v16, v20 offset0:64 offset1:65
	ds_write2_b32 v45, v17, v21 offset0:64 offset1:65
	ds_write2_b32 v46, v18, v22 offset0:64 offset1:65
	ds_write2_b32 v47, v19, v23 offset0:64 offset1:65
	ds_write2_b32 v44, v24, v28 offset0:96 offset1:97
	ds_write2_b32 v45, v25, v29 offset0:96 offset1:97
	ds_write2_b32 v46, v26, v30 offset0:96 offset1:97
	ds_write2_b32 v47, v27, v31 offset0:96 offset1:97
	ds_read_b64 v[0:1], v52 offset:0
	ds_read_b64 v[2:3], v52 offset:512
	ds_read_b64 v[4:5], v52 offset:1024
	ds_read_b64 v[6:7], v52 offset:1536
	ds_read_b64 v[8:9], v52 offset:2048
	ds_read_b64 v[10:11], v52 offset:2560
	ds_read_b64 v[12:13], v52 offset:3072
	ds_read_b64 v[14:15], v52 offset:3584
	ds_read_b64 v[16:17], v52 offset:4096
	ds_read_b64 v[18:19], v52 offset:4608
	ds_read_b64 v[20:21], v52 offset:5120
	ds_read_b64 v[22:23], v52 offset:5632
	ds_read_b64 v[24:25], v52 offset:6144
	ds_read_b64 v[26:27], v52 offset:6656
	ds_read_b64 v[28:29], v52 offset:7168
	ds_read_b64 v[30:31], v52 offset:7680
	s_waitcnt vmcnt(2)
	s_waitcnt lgkmcnt(15)
	v_fma_f32 v58, v36, v54, v0
	v_fma_f32 v59, v36, v55, v1
	v_mfma_f32_16x16x4_f32 v[112:115], v100, v64, 0
	v_mfma_f32_16x16x4_f32 v[116:119], v100, v65, 0
	v_fma_f32 v56, -v37, v55, v58
	v_fma_f32 v57, v37, v54, v59
	v_cvt_pk_bf16_f32 v62, v56, v57
	ds_write_b16 v60, v62 offset:0
	ds_write_b16_d16_hi v60, v62 offset:128
	s_waitcnt lgkmcnt(15)
	v_fma_f32 v58, v36, v56, v2
	v_fma_f32 v59, v36, v57, v3
	v_mfma_f32_16x16x4_f32 v[120:123], v100, v72, 0
	v_mfma_f32_16x16x4_f32 v[124:127], v100, v73, 0
	v_fma_f32 v54, -v37, v57, v58
	v_fma_f32 v55, v37, v56, v59
	v_cvt_pk_bf16_f32 v62, v54, v55
	ds_write_b16 v60, v62 offset:272
	ds_write_b16_d16_hi v60, v62 offset:400
	s_waitcnt lgkmcnt(15)
	v_fma_f32 v58, v36, v54, v4
	v_fma_f32 v59, v36, v55, v5
	v_mfma_f32_16x16x4_f32 v[128:131], v100, v80, 0
	v_mfma_f32_16x16x4_f32 v[132:135], v100, v81, 0
	v_fma_f32 v56, -v37, v55, v58
	v_fma_f32 v57, v37, v54, v59
	v_cvt_pk_bf16_f32 v62, v56, v57
	ds_write_b16 v60, v62 offset:544
	ds_write_b16_d16_hi v60, v62 offset:672
	s_waitcnt lgkmcnt(15)
	v_fma_f32 v58, v36, v56, v6
	v_fma_f32 v59, v36, v57, v7
	v_mfma_f32_16x16x4_f32 v[136:139], v100, v88, 0
	v_mfma_f32_16x16x4_f32 v[140:143], v100, v89, 0
	v_fma_f32 v54, -v37, v57, v58
	v_fma_f32 v55, v37, v56, v59
	v_cvt_pk_bf16_f32 v62, v54, v55
	ds_write_b16 v60, v62 offset:816
	ds_write_b16_d16_hi v60, v62 offset:944
	s_waitcnt lgkmcnt(15)
	v_fma_f32 v58, v36, v54, v8
	v_fma_f32 v59, v36, v55, v9
	v_mfma_f32_16x16x4_f32 v[112:115], v101, v66, v[112:115]
	v_mfma_f32_16x16x4_f32 v[116:119], v101, v67, v[116:119]
	v_fma_f32 v56, -v37, v55, v58
	v_fma_f32 v57, v37, v54, v59
	v_cvt_pk_bf16_f32 v62, v56, v57
	ds_write_b16 v60, v62 offset:1088
	ds_write_b16_d16_hi v60, v62 offset:1216
	s_waitcnt lgkmcnt(15)
	v_fma_f32 v58, v36, v56, v10
	v_fma_f32 v59, v36, v57, v11
	v_mfma_f32_16x16x4_f32 v[120:123], v101, v74, v[120:123]
	v_mfma_f32_16x16x4_f32 v[124:127], v101, v75, v[124:127]
	v_fma_f32 v54, -v37, v57, v58
	v_fma_f32 v55, v37, v56, v59
	v_cvt_pk_bf16_f32 v62, v54, v55
	ds_write_b16 v60, v62 offset:1360
	ds_write_b16_d16_hi v60, v62 offset:1488
	s_waitcnt lgkmcnt(15)
	v_fma_f32 v58, v36, v54, v12
	v_fma_f32 v59, v36, v55, v13
	v_mfma_f32_16x16x4_f32 v[128:131], v101, v82, v[128:131]
	v_mfma_f32_16x16x4_f32 v[132:135], v101, v83, v[132:135]
	v_fma_f32 v56, -v37, v55, v58
	v_fma_f32 v57, v37, v54, v59
	v_cvt_pk_bf16_f32 v62, v56, v57
	ds_write_b16 v60, v62 offset:1632
	ds_write_b16_d16_hi v60, v62 offset:1760
	s_waitcnt lgkmcnt(15)
; __device__ void phase_s5_pass2(CParams& p, int l, int item, char* smem) {
;     ...
;     for (int s = 0; s < 4; s++) {
;       const int sb = dir == 0 ? s : 3 - s;
;       for (int i = 0; i < 16; i++) {
;         int tl = dir == 0 ? i : 15 - i;
;         int t = sb * 16 + tl;
;         float u[16];
; #pragma unroll
;         for (int k = 0; k < 4; k++) {
;           float4 uv = *(const float4*)(us + t * 16 + k * 4);
;           u[k * 4] = uv.x; u[k * 4 + 1] = uv.y; u[k * 4 + 2] = uv.z; u[k * 4 + 3] = uv.w;
;         }
;         f32x2 bu = {0.f, 0.f};
; #pragma unroll
;         for (int cc = 0; cc < 16; cc++) bu = __builtin_elementwise_fma(bb[cc], f32x2{u[cc], u[cc]}, bu);
;         float nr = A.x * hr - A.y * hi + bu[0];
;         float ni = A.x * hi + A.y * hr + bu[1];
;         hr = nr; hi = ni;
;         hs[tl * 136 + lane] = f2bf(hr);
;         hs[tl * 136 + 64 + lane] = f2bf(hi);
;       }
;       __syncthreads();
; #pragma unroll
;       for (int ks = 0; ks < 4; ks++) {
;         bf16x8 a = *(const bf16x8*)(hs + l15 * 136 + ks * 32 + lq * 8);
;         acc[sb] = __builtin_amdgcn_mfma_f32_16x16x32_bf16(a, cf[ks], acc[sb], 0, 0, 0);
;       }
	v_fma_f32 v58, v36, v56, v14
	v_fma_f32 v59, v36, v57, v15
	v_mfma_f32_16x16x4_f32 v[136:139], v101, v90, v[136:139]
	v_mfma_f32_16x16x4_f32 v[140:143], v101, v91, v[140:143]
	v_fma_f32 v54, -v37, v57, v58
	v_fma_f32 v55, v37, v56, v59
	v_cvt_pk_bf16_f32 v62, v54, v55
	ds_write_b16 v60, v62 offset:1904
	ds_write_b16_d16_hi v60, v62 offset:2032
	s_waitcnt lgkmcnt(15)
	v_fma_f32 v58, v36, v54, v16
	v_fma_f32 v59, v36, v55, v17
	v_mfma_f32_16x16x4_f32 v[112:115], v102, v68, v[112:115]
	v_mfma_f32_16x16x4_f32 v[116:119], v102, v69, v[116:119]
	v_fma_f32 v56, -v37, v55, v58
	v_fma_f32 v57, v37, v54, v59
	v_cvt_pk_bf16_f32 v62, v56, v57
	ds_write_b16 v60, v62 offset:2176
	ds_write_b16_d16_hi v60, v62 offset:2304
	s_waitcnt lgkmcnt(15)
	v_fma_f32 v58, v36, v56, v18
	v_fma_f32 v59, v36, v57, v19
	v_mfma_f32_16x16x4_f32 v[120:123], v102, v76, v[120:123]
	v_mfma_f32_16x16x4_f32 v[124:127], v102, v77, v[124:127]
	v_fma_f32 v54, -v37, v57, v58
	v_fma_f32 v55, v37, v56, v59
	v_cvt_pk_bf16_f32 v62, v54, v55
	ds_write_b16 v60, v62 offset:2448
	ds_write_b16_d16_hi v60, v62 offset:2576
	s_waitcnt lgkmcnt(15)
	v_fma_f32 v58, v36, v54, v20
	v_fma_f32 v59, v36, v55, v21
	v_mfma_f32_16x16x4_f32 v[128:131], v102, v84, v[128:131]
	v_mfma_f32_16x16x4_f32 v[132:135], v102, v85, v[132:135]
	v_fma_f32 v56, -v37, v55, v58
	v_fma_f32 v57, v37, v54, v59
	v_cvt_pk_bf16_f32 v62, v56, v57
	ds_write_b16 v60, v62 offset:2720
	ds_write_b16_d16_hi v60, v62 offset:2848
	s_waitcnt lgkmcnt(15)
	v_fma_f32 v58, v36, v56, v22
	v_fma_f32 v59, v36, v57, v23
	v_mfma_f32_16x16x4_f32 v[136:139], v102, v92, v[136:139]
	v_mfma_f32_16x16x4_f32 v[140:143], v102, v93, v[140:143]
	v_fma_f32 v54, -v37, v57, v58
	v_fma_f32 v55, v37, v56, v59
	v_cvt_pk_bf16_f32 v62, v54, v55
	ds_write_b16 v60, v62 offset:2992
	ds_write_b16_d16_hi v60, v62 offset:3120
	s_waitcnt lgkmcnt(15)
	v_fma_f32 v58, v36, v54, v24
	v_fma_f32 v59, v36, v55, v25
	v_mfma_f32_16x16x4_f32 v[112:115], v103, v70, v[112:115]
	v_mfma_f32_16x16x4_f32 v[116:119], v103, v71, v[116:119]
	v_fma_f32 v56, -v37, v55, v58
	v_fma_f32 v57, v37, v54, v59
	v_cvt_pk_bf16_f32 v62, v56, v57
	ds_write_b16 v60, v62 offset:3264
	ds_write_b16_d16_hi v60, v62 offset:3392
	s_waitcnt lgkmcnt(15)
	v_fma_f32 v58, v36, v56, v26
	v_fma_f32 v59, v36, v57, v27
	v_mfma_f32_16x16x4_f32 v[120:123], v103, v78, v[120:123]
	v_mfma_f32_16x16x4_f32 v[124:127], v103, v79, v[124:127]
	v_fma_f32 v54, -v37, v57, v58
	v_fma_f32 v55, v37, v56, v59
	v_cvt_pk_bf16_f32 v62, v54, v55
	ds_write_b16 v60, v62 offset:3536
	ds_write_b16_d16_hi v60, v62 offset:3664
	s_waitcnt lgkmcnt(15)
	v_fma_f32 v58, v36, v54, v28
	v_fma_f32 v59, v36, v55, v29
	v_mfma_f32_16x16x4_f32 v[128:131], v103, v86, v[128:131]
	v_mfma_f32_16x16x4_f32 v[132:135], v103, v87, v[132:135]
	v_fma_f32 v56, -v37, v55, v58
	v_fma_f32 v57, v37, v54, v59
	v_cvt_pk_bf16_f32 v62, v56, v57
	ds_write_b16 v60, v62 offset:3808
	ds_write_b16_d16_hi v60, v62 offset:3936
	s_waitcnt lgkmcnt(15)
	v_fma_f32 v58, v36, v56, v30
	v_fma_f32 v59, v36, v57, v31
	v_mfma_f32_16x16x4_f32 v[136:139], v103, v94, v[136:139]
	v_mfma_f32_16x16x4_f32 v[140:143], v103, v95, v[140:143]
	v_fma_f32 v54, -v37, v57, v58
	v_fma_f32 v55, v37, v56, v59
	v_cvt_pk_bf16_f32 v62, v54, v55
	ds_write_b16 v60, v62 offset:4080
	ds_write_b16_d16_hi v60, v62 offset:4208
	ds_read_b128 v[184:187], v61 offset:0
	ds_read_b128 v[188:191], v61 offset:64
	ds_read_b128 v[192:195], v61 offset:128
	ds_read_b128 v[196:199], v61 offset:192
	s_waitcnt lgkmcnt(0)
	v_mfma_f32_16x16x32_bf16 v[148:151], v[184:187], v[168:171], v[148:151]
	v_mfma_f32_16x16x32_bf16 v[148:151], v[188:191], v[172:175], v[148:151]
	v_mfma_f32_16x16x32_bf16 v[148:151], v[192:195], v[176:179], v[148:151]
	v_mfma_f32_16x16x32_bf16 v[148:151], v[196:199], v[180:183], v[148:151]
	s_nop 15
	s_nop 15
	ds_write2_b32 v44, v112, v116 offset0:0 offset1:1
	ds_write2_b32 v45, v113, v117 offset0:0 offset1:1
	ds_write2_b32 v46, v114, v118 offset0:0 offset1:1
	ds_write2_b32 v47, v115, v119 offset0:0 offset1:1
	ds_write2_b32 v44, v120, v124 offset0:32 offset1:33
	ds_write2_b32 v45, v121, v125 offset0:32 offset1:33
	ds_write2_b32 v46, v122, v126 offset0:32 offset1:33
	ds_write2_b32 v47, v123, v127 offset0:32 offset1:33
	ds_write2_b32 v44, v128, v132 offset0:64 offset1:65
	ds_write2_b32 v45, v129, v133 offset0:64 offset1:65
	ds_write2_b32 v46, v130, v134 offset0:64 offset1:65
	ds_write2_b32 v47, v131, v135 offset0:64 offset1:65
	ds_write2_b32 v44, v136, v140 offset0:96 offset1:97
	ds_write2_b32 v45, v137, v141 offset0:96 offset1:97
	ds_write2_b32 v46, v138, v142 offset0:96 offset1:97
	ds_write2_b32 v47, v139, v143 offset0:96 offset1:97
	ds_read_b64 v[112:113], v52 offset:0
	ds_read_b64 v[114:115], v52 offset:512
	ds_read_b64 v[116:117], v52 offset:1024
	ds_read_b64 v[118:119], v52 offset:1536
	ds_read_b64 v[120:121], v52 offset:2048
	ds_read_b64 v[122:123], v52 offset:2560
	ds_read_b64 v[124:125], v52 offset:3072
	ds_read_b64 v[126:127], v52 offset:3584
	ds_read_b64 v[128:129], v52 offset:4096
	ds_read_b64 v[130:131], v52 offset:4608
	ds_read_b64 v[132:133], v52 offset:5120
	ds_read_b64 v[134:135], v52 offset:5632
	ds_read_b64 v[136:137], v52 offset:6144
	ds_read_b64 v[138:139], v52 offset:6656
	ds_read_b64 v[140:141], v52 offset:7168
	ds_read_b64 v[142:143], v52 offset:7680
	s_waitcnt vmcnt(1)
	s_waitcnt lgkmcnt(15)
	v_fma_f32 v58, v36, v54, v112
	v_fma_f32 v59, v36, v55, v113
	v_mfma_f32_16x16x4_f32 v[0:3], v104, v64, 0
	v_mfma_f32_16x16x4_f32 v[4:7], v104, v65, 0
	v_fma_f32 v56, -v37, v55, v58
	v_fma_f32 v57, v37, v54, v59
	v_cvt_pk_bf16_f32 v62, v56, v57
	ds_write_b16 v60, v62 offset:0
	ds_write_b16_d16_hi v60, v62 offset:128
	s_waitcnt lgkmcnt(15)
; __device__ void phase_s5_pass2(CParams& p, int l, int item, char* smem) {
;     ...
;     for (int s = 0; s < 4; s++) {
;       const int sb = dir == 0 ? s : 3 - s;
;       for (int i = 0; i < 16; i++) {
;         int tl = dir == 0 ? i : 15 - i;
;         int t = sb * 16 + tl;
;         float u[16];
; #pragma unroll
;         for (int k = 0; k < 4; k++) {
;           float4 uv = *(const float4*)(us + t * 16 + k * 4);
;           u[k * 4] = uv.x; u[k * 4 + 1] = uv.y; u[k * 4 + 2] = uv.z; u[k * 4 + 3] = uv.w;
;         }
;         f32x2 bu = {0.f, 0.f};
; #pragma unroll
;         for (int cc = 0; cc < 16; cc++) bu = __builtin_elementwise_fma(bb[cc], f32x2{u[cc], u[cc]}, bu);
;         float nr = A.x * hr - A.y * hi + bu[0];
;         float ni = A.x * hi + A.y * hr + bu[1];
;         hr = nr; hi = ni;
;         hs[tl * 136 + lane] = f2bf(hr);
;         hs[tl * 136 + 64 + lane] = f2bf(hi);
;       }
	v_fma_f32 v58, v36, v56, v114
	v_fma_f32 v59, v36, v57, v115
	v_mfma_f32_16x16x4_f32 v[8:11], v104, v72, 0
	v_mfma_f32_16x16x4_f32 v[12:15], v104, v73, 0
	v_fma_f32 v54, -v37, v57, v58
	v_fma_f32 v55, v37, v56, v59
	v_cvt_pk_bf16_f32 v62, v54, v55
	ds_write_b16 v60, v62 offset:272
	ds_write_b16_d16_hi v60, v62 offset:400
	s_waitcnt lgkmcnt(15)
	v_fma_f32 v58, v36, v54, v116
	v_fma_f32 v59, v36, v55, v117
	v_mfma_f32_16x16x4_f32 v[16:19], v104, v80, 0
	v_mfma_f32_16x16x4_f32 v[20:23], v104, v81, 0
	v_fma_f32 v56, -v37, v55, v58
	v_fma_f32 v57, v37, v54, v59
	v_cvt_pk_bf16_f32 v62, v56, v57
	ds_write_b16 v60, v62 offset:544
	ds_write_b16_d16_hi v60, v62 offset:672
	s_waitcnt lgkmcnt(15)
	v_fma_f32 v58, v36, v56, v118
	v_fma_f32 v59, v36, v57, v119
	v_mfma_f32_16x16x4_f32 v[24:27], v104, v88, 0
	v_mfma_f32_16x16x4_f32 v[28:31], v104, v89, 0
	v_fma_f32 v54, -v37, v57, v58
	v_fma_f32 v55, v37, v56, v59
	v_cvt_pk_bf16_f32 v62, v54, v55
	ds_write_b16 v60, v62 offset:816
	ds_write_b16_d16_hi v60, v62 offset:944
	s_waitcnt lgkmcnt(15)
	v_fma_f32 v58, v36, v54, v120
	v_fma_f32 v59, v36, v55, v121
	v_mfma_f32_16x16x4_f32 v[0:3], v105, v66, v[0:3]
	v_mfma_f32_16x16x4_f32 v[4:7], v105, v67, v[4:7]
	v_fma_f32 v56, -v37, v55, v58
	v_fma_f32 v57, v37, v54, v59
	v_cvt_pk_bf16_f32 v62, v56, v57
	ds_write_b16 v60, v62 offset:1088
	ds_write_b16_d16_hi v60, v62 offset:1216
	s_waitcnt lgkmcnt(15)
	v_fma_f32 v58, v36, v56, v122
	v_fma_f32 v59, v36, v57, v123
	v_mfma_f32_16x16x4_f32 v[8:11], v105, v74, v[8:11]
	v_mfma_f32_16x16x4_f32 v[12:15], v105, v75, v[12:15]
	v_fma_f32 v54, -v37, v57, v58
	v_fma_f32 v55, v37, v56, v59
	v_cvt_pk_bf16_f32 v62, v54, v55
	ds_write_b16 v60, v62 offset:1360
	ds_write_b16_d16_hi v60, v62 offset:1488
	s_waitcnt lgkmcnt(15)
	v_fma_f32 v58, v36, v54, v124
	v_fma_f32 v59, v36, v55, v125
	v_mfma_f32_16x16x4_f32 v[16:19], v105, v82, v[16:19]
	v_mfma_f32_16x16x4_f32 v[20:23], v105, v83, v[20:23]
	v_fma_f32 v56, -v37, v55, v58
	v_fma_f32 v57, v37, v54, v59
	v_cvt_pk_bf16_f32 v62, v56, v57
	ds_write_b16 v60, v62 offset:1632
	ds_write_b16_d16_hi v60, v62 offset:1760
	s_waitcnt lgkmcnt(15)
	v_fma_f32 v58, v36, v56, v126
	v_fma_f32 v59, v36, v57, v127
	v_mfma_f32_16x16x4_f32 v[24:27], v105, v90, v[24:27]
	v_mfma_f32_16x16x4_f32 v[28:31], v105, v91, v[28:31]
	v_fma_f32 v54, -v37, v57, v58
	v_fma_f32 v55, v37, v56, v59
	v_cvt_pk_bf16_f32 v62, v54, v55
	ds_write_b16 v60, v62 offset:1904
	ds_write_b16_d16_hi v60, v62 offset:2032
	s_waitcnt lgkmcnt(15)
	v_fma_f32 v58, v36, v54, v128
	v_fma_f32 v59, v36, v55, v129
	v_mfma_f32_16x16x4_f32 v[0:3], v106, v68, v[0:3]
	v_mfma_f32_16x16x4_f32 v[4:7], v106, v69, v[4:7]
	v_fma_f32 v56, -v37, v55, v58
	v_fma_f32 v57, v37, v54, v59
	v_cvt_pk_bf16_f32 v62, v56, v57
	ds_write_b16 v60, v62 offset:2176
	ds_write_b16_d16_hi v60, v62 offset:2304
	s_waitcnt lgkmcnt(15)
	v_fma_f32 v58, v36, v56, v130
	v_fma_f32 v59, v36, v57, v131
	v_mfma_f32_16x16x4_f32 v[8:11], v106, v76, v[8:11]
	v_mfma_f32_16x16x4_f32 v[12:15], v106, v77, v[12:15]
	v_fma_f32 v54, -v37, v57, v58
	v_fma_f32 v55, v37, v56, v59
	v_cvt_pk_bf16_f32 v62, v54, v55
	ds_write_b16 v60, v62 offset:2448
	ds_write_b16_d16_hi v60, v62 offset:2576
	s_waitcnt lgkmcnt(15)
	v_fma_f32 v58, v36, v54, v132
	v_fma_f32 v59, v36, v55, v133
	v_mfma_f32_16x16x4_f32 v[16:19], v106, v84, v[16:19]
	v_mfma_f32_16x16x4_f32 v[20:23], v106, v85, v[20:23]
	v_fma_f32 v56, -v37, v55, v58
	v_fma_f32 v57, v37, v54, v59
	v_cvt_pk_bf16_f32 v62, v56, v57
	ds_write_b16 v60, v62 offset:2720
	ds_write_b16_d16_hi v60, v62 offset:2848
	s_waitcnt lgkmcnt(15)
	v_fma_f32 v58, v36, v56, v134
	v_fma_f32 v59, v36, v57, v135
	v_mfma_f32_16x16x4_f32 v[24:27], v106, v92, v[24:27]
	v_mfma_f32_16x16x4_f32 v[28:31], v106, v93, v[28:31]
	v_fma_f32 v54, -v37, v57, v58
	v_fma_f32 v55, v37, v56, v59
	v_cvt_pk_bf16_f32 v62, v54, v55
	ds_write_b16 v60, v62 offset:2992
	ds_write_b16_d16_hi v60, v62 offset:3120
	s_waitcnt lgkmcnt(15)
	v_fma_f32 v58, v36, v54, v136
	v_fma_f32 v59, v36, v55, v137
	v_mfma_f32_16x16x4_f32 v[0:3], v107, v70, v[0:3]
	v_mfma_f32_16x16x4_f32 v[4:7], v107, v71, v[4:7]
	v_fma_f32 v56, -v37, v55, v58
	v_fma_f32 v57, v37, v54, v59
	v_cvt_pk_bf16_f32 v62, v56, v57
	ds_write_b16 v60, v62 offset:3264
	ds_write_b16_d16_hi v60, v62 offset:3392
	s_waitcnt lgkmcnt(15)
	v_fma_f32 v58, v36, v56, v138
	v_fma_f32 v59, v36, v57, v139
	v_mfma_f32_16x16x4_f32 v[8:11], v107, v78, v[8:11]
	v_mfma_f32_16x16x4_f32 v[12:15], v107, v79, v[12:15]
	v_fma_f32 v54, -v37, v57, v58
	v_fma_f32 v55, v37, v56, v59
	v_cvt_pk_bf16_f32 v62, v54, v55
	ds_write_b16 v60, v62 offset:3536
	ds_write_b16_d16_hi v60, v62 offset:3664
	s_waitcnt lgkmcnt(15)
	v_fma_f32 v58, v36, v54, v140
	v_fma_f32 v59, v36, v55, v141
	v_mfma_f32_16x16x4_f32 v[16:19], v107, v86, v[16:19]
	v_mfma_f32_16x16x4_f32 v[20:23], v107, v87, v[20:23]
	v_fma_f32 v56, -v37, v55, v58
	v_fma_f32 v57, v37, v54, v59
	v_cvt_pk_bf16_f32 v62, v56, v57
	ds_write_b16 v60, v62 offset:3808
	ds_write_b16_d16_hi v60, v62 offset:3936
	s_waitcnt lgkmcnt(15)
	v_fma_f32 v58, v36, v56, v142
	v_fma_f32 v59, v36, v57, v143
	v_mfma_f32_16x16x4_f32 v[24:27], v107, v94, v[24:27]
	v_mfma_f32_16x16x4_f32 v[28:31], v107, v95, v[28:31]
	v_fma_f32 v54, -v37, v57, v58
	v_fma_f32 v55, v37, v56, v59
	v_cvt_pk_bf16_f32 v62, v54, v55
	ds_write_b16 v60, v62 offset:4080
	ds_write_b16_d16_hi v60, v62 offset:4208
	ds_read_b128 v[184:187], v61 offset:0
	ds_read_b128 v[188:191], v61 offset:64
	ds_read_b128 v[192:195], v61 offset:128
	ds_read_b128 v[196:199], v61 offset:192
	s_waitcnt lgkmcnt(0)
; __device__ void phase_s5_pass2(CParams& p, int l, int item, char* smem) {
;     ...
;       for (int i = 0; i < 16; i++) {
;         int tl = dir == 0 ? i : 15 - i;
;         int t = sb * 16 + tl;
;         float u[16];
; #pragma unroll
;         for (int k = 0; k < 4; k++) {
;           float4 uv = *(const float4*)(us + t * 16 + k * 4);
;           u[k * 4] = uv.x; u[k * 4 + 1] = uv.y; u[k * 4 + 2] = uv.z; u[k * 4 + 3] = uv.w;
;         }
;         f32x2 bu = {0.f, 0.f};
; #pragma unroll
;         for (int cc = 0; cc < 16; cc++) bu = __builtin_elementwise_fma(bb[cc], f32x2{u[cc], u[cc]}, bu);
;         float nr = A.x * hr - A.y * hi + bu[0];
;         float ni = A.x * hi + A.y * hr + bu[1];
;         hr = nr; hi = ni;
;         hs[tl * 136 + lane] = f2bf(hr);
;         hs[tl * 136 + 64 + lane] = f2bf(hi);
;       }
;       __syncthreads();
; #pragma unroll
;       for (int ks = 0; ks < 4; ks++) {
;         bf16x8 a = *(const bf16x8*)(hs + l15 * 136 + ks * 32 + lq * 8);
;         acc[sb] = __builtin_amdgcn_mfma_f32_16x16x32_bf16(a, cf[ks], acc[sb], 0, 0, 0);
;       }
	v_mfma_f32_16x16x32_bf16 v[152:155], v[184:187], v[168:171], v[152:155]
	v_mfma_f32_16x16x32_bf16 v[152:155], v[188:191], v[172:175], v[152:155]
	v_mfma_f32_16x16x32_bf16 v[152:155], v[192:195], v[176:179], v[152:155]
	v_mfma_f32_16x16x32_bf16 v[152:155], v[196:199], v[180:183], v[152:155]
	s_nop 15
	s_nop 15
	ds_write2_b32 v44, v0, v4 offset0:0 offset1:1
	ds_write2_b32 v45, v1, v5 offset0:0 offset1:1
	ds_write2_b32 v46, v2, v6 offset0:0 offset1:1
	ds_write2_b32 v47, v3, v7 offset0:0 offset1:1
	ds_write2_b32 v44, v8, v12 offset0:32 offset1:33
	ds_write2_b32 v45, v9, v13 offset0:32 offset1:33
	ds_write2_b32 v46, v10, v14 offset0:32 offset1:33
	ds_write2_b32 v47, v11, v15 offset0:32 offset1:33
	ds_write2_b32 v44, v16, v20 offset0:64 offset1:65
	ds_write2_b32 v45, v17, v21 offset0:64 offset1:65
	ds_write2_b32 v46, v18, v22 offset0:64 offset1:65
	ds_write2_b32 v47, v19, v23 offset0:64 offset1:65
	ds_write2_b32 v44, v24, v28 offset0:96 offset1:97
	ds_write2_b32 v45, v25, v29 offset0:96 offset1:97
	ds_write2_b32 v46, v26, v30 offset0:96 offset1:97
	ds_write2_b32 v47, v27, v31 offset0:96 offset1:97
	ds_read_b64 v[0:1], v52 offset:0
	ds_read_b64 v[2:3], v52 offset:512
	ds_read_b64 v[4:5], v52 offset:1024
	ds_read_b64 v[6:7], v52 offset:1536
	ds_read_b64 v[8:9], v52 offset:2048
	ds_read_b64 v[10:11], v52 offset:2560
	ds_read_b64 v[12:13], v52 offset:3072
	ds_read_b64 v[14:15], v52 offset:3584
	ds_read_b64 v[16:17], v52 offset:4096
	ds_read_b64 v[18:19], v52 offset:4608
	ds_read_b64 v[20:21], v52 offset:5120
	ds_read_b64 v[22:23], v52 offset:5632
	ds_read_b64 v[24:25], v52 offset:6144
	ds_read_b64 v[26:27], v52 offset:6656
	ds_read_b64 v[28:29], v52 offset:7168
	ds_read_b64 v[30:31], v52 offset:7680
	s_waitcnt vmcnt(0)
	s_waitcnt lgkmcnt(15)
	v_fma_f32 v58, v36, v54, v0
	v_fma_f32 v59, v36, v55, v1
	v_mfma_f32_16x16x4_f32 v[112:115], v108, v64, 0
	v_mfma_f32_16x16x4_f32 v[116:119], v108, v65, 0
	v_fma_f32 v56, -v37, v55, v58
	v_fma_f32 v57, v37, v54, v59
	v_cvt_pk_bf16_f32 v62, v56, v57
	ds_write_b16 v60, v62 offset:0
	ds_write_b16_d16_hi v60, v62 offset:128
	s_waitcnt lgkmcnt(15)
	v_fma_f32 v58, v36, v56, v2
	v_fma_f32 v59, v36, v57, v3
	v_mfma_f32_16x16x4_f32 v[120:123], v108, v72, 0
	v_mfma_f32_16x16x4_f32 v[124:127], v108, v73, 0
	v_fma_f32 v54, -v37, v57, v58
	v_fma_f32 v55, v37, v56, v59
	v_cvt_pk_bf16_f32 v62, v54, v55
	ds_write_b16 v60, v62 offset:272
	ds_write_b16_d16_hi v60, v62 offset:400
	s_waitcnt lgkmcnt(15)
	v_fma_f32 v58, v36, v54, v4
	v_fma_f32 v59, v36, v55, v5
	v_mfma_f32_16x16x4_f32 v[128:131], v108, v80, 0
	v_mfma_f32_16x16x4_f32 v[132:135], v108, v81, 0
	v_fma_f32 v56, -v37, v55, v58
	v_fma_f32 v57, v37, v54, v59
	v_cvt_pk_bf16_f32 v62, v56, v57
	ds_write_b16 v60, v62 offset:544
	ds_write_b16_d16_hi v60, v62 offset:672
	s_waitcnt lgkmcnt(15)
	v_fma_f32 v58, v36, v56, v6
	v_fma_f32 v59, v36, v57, v7
	v_mfma_f32_16x16x4_f32 v[136:139], v108, v88, 0
	v_mfma_f32_16x16x4_f32 v[140:143], v108, v89, 0
	v_fma_f32 v54, -v37, v57, v58
	v_fma_f32 v55, v37, v56, v59
	v_cvt_pk_bf16_f32 v62, v54, v55
	ds_write_b16 v60, v62 offset:816
	ds_write_b16_d16_hi v60, v62 offset:944
	s_waitcnt lgkmcnt(15)
	v_fma_f32 v58, v36, v54, v8
	v_fma_f32 v59, v36, v55, v9
	v_mfma_f32_16x16x4_f32 v[112:115], v109, v66, v[112:115]
	v_mfma_f32_16x16x4_f32 v[116:119], v109, v67, v[116:119]
	v_fma_f32 v56, -v37, v55, v58
	v_fma_f32 v57, v37, v54, v59
	v_cvt_pk_bf16_f32 v62, v56, v57
	ds_write_b16 v60, v62 offset:1088
	ds_write_b16_d16_hi v60, v62 offset:1216
	s_waitcnt lgkmcnt(15)
	v_fma_f32 v58, v36, v56, v10
	v_fma_f32 v59, v36, v57, v11
	v_mfma_f32_16x16x4_f32 v[120:123], v109, v74, v[120:123]
	v_mfma_f32_16x16x4_f32 v[124:127], v109, v75, v[124:127]
	v_fma_f32 v54, -v37, v57, v58
	v_fma_f32 v55, v37, v56, v59
	v_cvt_pk_bf16_f32 v62, v54, v55
	ds_write_b16 v60, v62 offset:1360
	ds_write_b16_d16_hi v60, v62 offset:1488
	s_waitcnt lgkmcnt(15)
	v_fma_f32 v58, v36, v54, v12
	v_fma_f32 v59, v36, v55, v13
	v_mfma_f32_16x16x4_f32 v[128:131], v109, v82, v[128:131]
	v_mfma_f32_16x16x4_f32 v[132:135], v109, v83, v[132:135]
	v_fma_f32 v56, -v37, v55, v58
	v_fma_f32 v57, v37, v54, v59
	v_cvt_pk_bf16_f32 v62, v56, v57
	ds_write_b16 v60, v62 offset:1632
	ds_write_b16_d16_hi v60, v62 offset:1760
	s_waitcnt lgkmcnt(15)
	v_fma_f32 v58, v36, v56, v14
	v_fma_f32 v59, v36, v57, v15
	v_mfma_f32_16x16x4_f32 v[136:139], v109, v90, v[136:139]
	v_mfma_f32_16x16x4_f32 v[140:143], v109, v91, v[140:143]
	v_fma_f32 v54, -v37, v57, v58
	v_fma_f32 v55, v37, v56, v59
	v_cvt_pk_bf16_f32 v62, v54, v55
	ds_write_b16 v60, v62 offset:1904
	ds_write_b16_d16_hi v60, v62 offset:2032
	s_waitcnt lgkmcnt(15)
	v_fma_f32 v58, v36, v54, v16
	v_fma_f32 v59, v36, v55, v17
	v_mfma_f32_16x16x4_f32 v[112:115], v110, v68, v[112:115]
	v_mfma_f32_16x16x4_f32 v[116:119], v110, v69, v[116:119]
	v_fma_f32 v56, -v37, v55, v58
	v_fma_f32 v57, v37, v54, v59
	v_cvt_pk_bf16_f32 v62, v56, v57
	ds_write_b16 v60, v62 offset:2176
	ds_write_b16_d16_hi v60, v62 offset:2304
	s_waitcnt lgkmcnt(15)
	v_fma_f32 v58, v36, v56, v18
	v_fma_f32 v59, v36, v57, v19
	v_mfma_f32_16x16x4_f32 v[120:123], v110, v76, v[120:123]
	v_mfma_f32_16x16x4_f32 v[124:127], v110, v77, v[124:127]
	v_fma_f32 v54, -v37, v57, v58
	v_fma_f32 v55, v37, v56, v59
	v_cvt_pk_bf16_f32 v62, v54, v55
	ds_write_b16 v60, v62 offset:2448
	ds_write_b16_d16_hi v60, v62 offset:2576
	s_waitcnt lgkmcnt(15)
	v_fma_f32 v58, v36, v54, v20
	v_fma_f32 v59, v36, v55, v21
	v_mfma_f32_16x16x4_f32 v[128:131], v110, v84, v[128:131]
	v_mfma_f32_16x16x4_f32 v[132:135], v110, v85, v[132:135]
	v_fma_f32 v56, -v37, v55, v58
	v_fma_f32 v57, v37, v54, v59
	v_cvt_pk_bf16_f32 v62, v56, v57
	ds_write_b16 v60, v62 offset:2720
	ds_write_b16_d16_hi v60, v62 offset:2848
	s_waitcnt lgkmcnt(15)
; __device__ void phase_s5_pass2(CParams& p, int l, int item, char* smem) {
;     ...
;     for (int s = 0; s < 4; s++) {
;       const int sb = dir == 0 ? s : 3 - s;
;       for (int i = 0; i < 16; i++) {
;         int tl = dir == 0 ? i : 15 - i;
;         int t = sb * 16 + tl;
;         float u[16];
; #pragma unroll
;         for (int k = 0; k < 4; k++) {
;           float4 uv = *(const float4*)(us + t * 16 + k * 4);
;           u[k * 4] = uv.x; u[k * 4 + 1] = uv.y; u[k * 4 + 2] = uv.z; u[k * 4 + 3] = uv.w;
;         }
;         f32x2 bu = {0.f, 0.f};
; #pragma unroll
;         for (int cc = 0; cc < 16; cc++) bu = __builtin_elementwise_fma(bb[cc], f32x2{u[cc], u[cc]}, bu);
;         float nr = A.x * hr - A.y * hi + bu[0];
;         float ni = A.x * hi + A.y * hr + bu[1];
;         hr = nr; hi = ni;
;         hs[tl * 136 + lane] = f2bf(hr);
;         hs[tl * 136 + 64 + lane] = f2bf(hi);
;       }
;       __syncthreads();
; #pragma unroll
;       for (int ks = 0; ks < 4; ks++) {
;         bf16x8 a = *(const bf16x8*)(hs + l15 * 136 + ks * 32 + lq * 8);
;         acc[sb] = __builtin_amdgcn_mfma_f32_16x16x32_bf16(a, cf[ks], acc[sb], 0, 0, 0);
;       }
	v_fma_f32 v58, v36, v56, v22
	v_fma_f32 v59, v36, v57, v23
	v_mfma_f32_16x16x4_f32 v[136:139], v110, v92, v[136:139]
	v_mfma_f32_16x16x4_f32 v[140:143], v110, v93, v[140:143]
	v_fma_f32 v54, -v37, v57, v58
	v_fma_f32 v55, v37, v56, v59
	v_cvt_pk_bf16_f32 v62, v54, v55
	ds_write_b16 v60, v62 offset:2992
	ds_write_b16_d16_hi v60, v62 offset:3120
	s_waitcnt lgkmcnt(15)
	v_fma_f32 v58, v36, v54, v24
	v_fma_f32 v59, v36, v55, v25
	v_mfma_f32_16x16x4_f32 v[112:115], v111, v70, v[112:115]
	v_mfma_f32_16x16x4_f32 v[116:119], v111, v71, v[116:119]
	v_fma_f32 v56, -v37, v55, v58
	v_fma_f32 v57, v37, v54, v59
	v_cvt_pk_bf16_f32 v62, v56, v57
	ds_write_b16 v60, v62 offset:3264
	ds_write_b16_d16_hi v60, v62 offset:3392
	s_waitcnt lgkmcnt(15)
	v_fma_f32 v58, v36, v56, v26
	v_fma_f32 v59, v36, v57, v27
	v_mfma_f32_16x16x4_f32 v[120:123], v111, v78, v[120:123]
	v_mfma_f32_16x16x4_f32 v[124:127], v111, v79, v[124:127]
	v_fma_f32 v54, -v37, v57, v58
	v_fma_f32 v55, v37, v56, v59
	v_cvt_pk_bf16_f32 v62, v54, v55
	ds_write_b16 v60, v62 offset:3536
	ds_write_b16_d16_hi v60, v62 offset:3664
	s_waitcnt lgkmcnt(15)
	v_fma_f32 v58, v36, v54, v28
	v_fma_f32 v59, v36, v55, v29
	v_mfma_f32_16x16x4_f32 v[128:131], v111, v86, v[128:131]
	v_mfma_f32_16x16x4_f32 v[132:135], v111, v87, v[132:135]
	v_fma_f32 v56, -v37, v55, v58
	v_fma_f32 v57, v37, v54, v59
	v_cvt_pk_bf16_f32 v62, v56, v57
	ds_write_b16 v60, v62 offset:3808
	ds_write_b16_d16_hi v60, v62 offset:3936
	s_waitcnt lgkmcnt(15)
	v_fma_f32 v58, v36, v56, v30
	v_fma_f32 v59, v36, v57, v31
	v_mfma_f32_16x16x4_f32 v[136:139], v111, v94, v[136:139]
	v_mfma_f32_16x16x4_f32 v[140:143], v111, v95, v[140:143]
	v_fma_f32 v54, -v37, v57, v58
	v_fma_f32 v55, v37, v56, v59
	v_cvt_pk_bf16_f32 v62, v54, v55
	ds_write_b16 v60, v62 offset:4080
	ds_write_b16_d16_hi v60, v62 offset:4208
	ds_read_b128 v[184:187], v61 offset:0
	ds_read_b128 v[188:191], v61 offset:64
	ds_read_b128 v[192:195], v61 offset:128
	ds_read_b128 v[196:199], v61 offset:192
	s_waitcnt lgkmcnt(0)
	v_mfma_f32_16x16x32_bf16 v[156:159], v[184:187], v[168:171], v[156:159]
	v_mfma_f32_16x16x32_bf16 v[156:159], v[188:191], v[172:175], v[156:159]
	v_mfma_f32_16x16x32_bf16 v[156:159], v[192:195], v[176:179], v[156:159]
	v_mfma_f32_16x16x32_bf16 v[156:159], v[196:199], v[180:183], v[156:159]
	s_nop 15
	s_nop 15
	ds_write2_b32 v44, v112, v116 offset0:0 offset1:1
	ds_write2_b32 v45, v113, v117 offset0:0 offset1:1
	ds_write2_b32 v46, v114, v118 offset0:0 offset1:1
	ds_write2_b32 v47, v115, v119 offset0:0 offset1:1
	ds_write2_b32 v44, v120, v124 offset0:32 offset1:33
	ds_write2_b32 v45, v121, v125 offset0:32 offset1:33
	ds_write2_b32 v46, v122, v126 offset0:32 offset1:33
	ds_write2_b32 v47, v123, v127 offset0:32 offset1:33
	ds_write2_b32 v44, v128, v132 offset0:64 offset1:65
	ds_write2_b32 v45, v129, v133 offset0:64 offset1:65
	ds_write2_b32 v46, v130, v134 offset0:64 offset1:65
	ds_write2_b32 v47, v131, v135 offset0:64 offset1:65
	ds_write2_b32 v44, v136, v140 offset0:96 offset1:97
	ds_write2_b32 v45, v137, v141 offset0:96 offset1:97
	ds_write2_b32 v46, v138, v142 offset0:96 offset1:97
	ds_write2_b32 v47, v139, v143 offset0:96 offset1:97
	ds_read_b64 v[112:113], v52 offset:0
	ds_read_b64 v[114:115], v52 offset:512
	ds_read_b64 v[116:117], v52 offset:1024
	ds_read_b64 v[118:119], v52 offset:1536
	ds_read_b64 v[120:121], v52 offset:2048
	ds_read_b64 v[122:123], v52 offset:2560
	ds_read_b64 v[124:125], v52 offset:3072
	ds_read_b64 v[126:127], v52 offset:3584
	ds_read_b64 v[128:129], v52 offset:4096
	ds_read_b64 v[130:131], v52 offset:4608
	ds_read_b64 v[132:133], v52 offset:5120
	ds_read_b64 v[134:135], v52 offset:5632
	ds_read_b64 v[136:137], v52 offset:6144
	ds_read_b64 v[138:139], v52 offset:6656
	ds_read_b64 v[140:141], v52 offset:7168
	ds_read_b64 v[142:143], v52 offset:7680
	s_waitcnt lgkmcnt(15)
	v_fma_f32 v58, v36, v54, v112
	v_fma_f32 v59, v36, v55, v113
	v_fma_f32 v56, -v37, v55, v58
	v_fma_f32 v57, v37, v54, v59
	v_cvt_pk_bf16_f32 v62, v56, v57
	ds_write_b16 v60, v62 offset:0
	ds_write_b16_d16_hi v60, v62 offset:128
	s_waitcnt lgkmcnt(15)
	v_fma_f32 v58, v36, v56, v114
	v_fma_f32 v59, v36, v57, v115
	v_fma_f32 v54, -v37, v57, v58
	v_fma_f32 v55, v37, v56, v59
	v_cvt_pk_bf16_f32 v62, v54, v55
	ds_write_b16 v60, v62 offset:272
	ds_write_b16_d16_hi v60, v62 offset:400
	s_waitcnt lgkmcnt(15)
	v_fma_f32 v58, v36, v54, v116
	v_fma_f32 v59, v36, v55, v117
	v_fma_f32 v56, -v37, v55, v58
	v_fma_f32 v57, v37, v54, v59
	v_cvt_pk_bf16_f32 v62, v56, v57
	ds_write_b16 v60, v62 offset:544
	ds_write_b16_d16_hi v60, v62 offset:672
	s_waitcnt lgkmcnt(15)
	v_fma_f32 v58, v36, v56, v118
	v_fma_f32 v59, v36, v57, v119
	v_fma_f32 v54, -v37, v57, v58
	v_fma_f32 v55, v37, v56, v59
	v_cvt_pk_bf16_f32 v62, v54, v55
	ds_write_b16 v60, v62 offset:816
	ds_write_b16_d16_hi v60, v62 offset:944
	s_waitcnt lgkmcnt(15)
	v_fma_f32 v58, v36, v54, v120
	v_fma_f32 v59, v36, v55, v121
	v_fma_f32 v56, -v37, v55, v58
	v_fma_f32 v57, v37, v54, v59
	v_cvt_pk_bf16_f32 v62, v56, v57
	ds_write_b16 v60, v62 offset:1088
	ds_write_b16_d16_hi v60, v62 offset:1216
	s_waitcnt lgkmcnt(15)
	v_fma_f32 v58, v36, v56, v122
	v_fma_f32 v59, v36, v57, v123
	v_fma_f32 v54, -v37, v57, v58
	v_fma_f32 v55, v37, v56, v59
	v_cvt_pk_bf16_f32 v62, v54, v55
	ds_write_b16 v60, v62 offset:1360
	ds_write_b16_d16_hi v60, v62 offset:1488
	s_waitcnt lgkmcnt(15)
	v_fma_f32 v58, v36, v54, v124
	v_fma_f32 v59, v36, v55, v125
	v_fma_f32 v56, -v37, v55, v58
	v_fma_f32 v57, v37, v54, v59
	v_cvt_pk_bf16_f32 v62, v56, v57
	ds_write_b16 v60, v62 offset:1632
	ds_write_b16_d16_hi v60, v62 offset:1760
	s_waitcnt lgkmcnt(15)
; __device__ void phase_s5_pass2(CParams& p, int l, int item, char* smem) {
;     ...
;     int pidx = ((l * 2 + dir) * 16 + g) * 64 + lane;
;     float2 A = p.Apar[pidx];
;     f32x2 bb[16];
; #pragma unroll
;     for (int cc = 0; cc < 16; cc++) {
;       float2 b = p.Bbar[(size_t)pidx * 16 + cc];
;       bb[cc] = f32x2{b.x, b.y};
;     }
;     bf16x8 cf[4];
; #pragma unroll
;     for (int ks = 0; ks < 4; ks++) {
;       int k = ks * 32 + lq * 8;
;       bool im = k >= 64;
;       const float* src = (im ? p.c_im : p.c_re) + ((((size_t)(l * 2 + dir) * 16 + g) * 16 + l15) * 64) + (k & 63);
;       float4 v0 = *(const float4*)src, v1 = *(const float4*)(src + 4);
;       float sgn = im ? -1.f : 1.f;
;       cf[ks][0] = (short)f2bf(sgn * v0.x); cf[ks][1] = (short)f2bf(sgn * v0.y);
;       cf[ks][2] = (short)f2bf(sgn * v0.z); cf[ks][3] = (short)f2bf(sgn * v0.w);
;       cf[ks][4] = (short)f2bf(sgn * v1.x); cf[ks][5] = (short)f2bf(sgn * v1.y);
;       cf[ks][6] = (short)f2bf(sgn * v1.z); cf[ks][7] = (short)f2bf(sgn * v1.w);
;     }
;     float2 h0 = p.Hin[(((size_t)q * 2 + dir) * 16 + g) * 64 + lane];
;     ...
;         float nr = A.x * hr - A.y * hi + bu[0];
;         float ni = A.x * hi + A.y * hr + bu[1];
;         hr = nr; hi = ni;
;         hs[tl * 136 + lane] = f2bf(hr);
;         hs[tl * 136 + 64 + lane] = f2bf(hi);
;       }
;       __syncthreads();
; #pragma unroll
;       for (int ks = 0; ks < 4; ks++) {
;         bf16x8 a = *(const bf16x8*)(hs + l15 * 136 + ks * 32 + lq * 8);
;         acc[sb] = __builtin_amdgcn_mfma_f32_16x16x32_bf16(a, cf[ks], acc[sb], 0, 0, 0);
	v_fma_f32 v58, v36, v56, v126
	v_fma_f32 v59, v36, v57, v127
	v_fma_f32 v54, -v37, v57, v58
	v_fma_f32 v55, v37, v56, v59
	v_cvt_pk_bf16_f32 v62, v54, v55
	ds_write_b16 v60, v62 offset:1904
	ds_write_b16_d16_hi v60, v62 offset:2032
	s_waitcnt lgkmcnt(15)
	v_fma_f32 v58, v36, v54, v128
	v_fma_f32 v59, v36, v55, v129
	v_fma_f32 v56, -v37, v55, v58
	v_fma_f32 v57, v37, v54, v59
	v_cvt_pk_bf16_f32 v62, v56, v57
	ds_write_b16 v60, v62 offset:2176
	ds_write_b16_d16_hi v60, v62 offset:2304
	s_waitcnt lgkmcnt(15)
	v_fma_f32 v58, v36, v56, v130
	v_fma_f32 v59, v36, v57, v131
	v_fma_f32 v54, -v37, v57, v58
	v_fma_f32 v55, v37, v56, v59
	v_cvt_pk_bf16_f32 v62, v54, v55
	ds_write_b16 v60, v62 offset:2448
	ds_write_b16_d16_hi v60, v62 offset:2576
	s_waitcnt lgkmcnt(15)
	v_fma_f32 v58, v36, v54, v132
	v_fma_f32 v59, v36, v55, v133
	v_fma_f32 v56, -v37, v55, v58
	v_fma_f32 v57, v37, v54, v59
	v_cvt_pk_bf16_f32 v62, v56, v57
	ds_write_b16 v60, v62 offset:2720
	ds_write_b16_d16_hi v60, v62 offset:2848
	s_waitcnt lgkmcnt(15)
	v_fma_f32 v58, v36, v56, v134
	v_fma_f32 v59, v36, v57, v135
	v_fma_f32 v54, -v37, v57, v58
	v_fma_f32 v55, v37, v56, v59
	v_cvt_pk_bf16_f32 v62, v54, v55
	ds_write_b16 v60, v62 offset:2992
	ds_write_b16_d16_hi v60, v62 offset:3120
	s_waitcnt lgkmcnt(15)
	v_fma_f32 v58, v36, v54, v136
	v_fma_f32 v59, v36, v55, v137
	v_fma_f32 v56, -v37, v55, v58
	v_fma_f32 v57, v37, v54, v59
	v_cvt_pk_bf16_f32 v62, v56, v57
	ds_write_b16 v60, v62 offset:3264
	ds_write_b16_d16_hi v60, v62 offset:3392
	s_waitcnt lgkmcnt(15)
	v_fma_f32 v58, v36, v56, v138
	v_fma_f32 v59, v36, v57, v139
	v_fma_f32 v54, -v37, v57, v58
	v_fma_f32 v55, v37, v56, v59
	v_cvt_pk_bf16_f32 v62, v54, v55
	ds_write_b16 v60, v62 offset:3536
	ds_write_b16_d16_hi v60, v62 offset:3664
	s_waitcnt lgkmcnt(15)
	v_fma_f32 v58, v36, v54, v140
	v_fma_f32 v59, v36, v55, v141
	v_fma_f32 v56, -v37, v55, v58
	v_fma_f32 v57, v37, v54, v59
	v_cvt_pk_bf16_f32 v62, v56, v57
	ds_write_b16 v60, v62 offset:3808
	ds_write_b16_d16_hi v60, v62 offset:3936
	s_waitcnt lgkmcnt(15)
	v_fma_f32 v58, v36, v56, v142
	v_fma_f32 v59, v36, v57, v143
	v_fma_f32 v54, -v37, v57, v58
	v_fma_f32 v55, v37, v56, v59
	v_cvt_pk_bf16_f32 v62, v54, v55
	ds_write_b16 v60, v62 offset:4080
	ds_write_b16_d16_hi v60, v62 offset:4208
	ds_read_b128 v[184:187], v61 offset:0
	ds_read_b128 v[188:191], v61 offset:64
	ds_read_b128 v[192:195], v61 offset:128
	ds_read_b128 v[196:199], v61 offset:192
	s_waitcnt lgkmcnt(0)
	v_mfma_f32_16x16x32_bf16 v[160:163], v[184:187], v[168:171], v[160:163]
	v_mfma_f32_16x16x32_bf16 v[160:163], v[188:191], v[172:175], v[160:163]
	v_mfma_f32_16x16x32_bf16 v[160:163], v[192:195], v[176:179], v[160:163]
	v_mfma_f32_16x16x32_bf16 v[160:163], v[196:199], v[180:183], v[160:163]
	s_lshl_b32 s20, s12, 1
	s_add_u32 s20, s20, 1
	s_lshl_b32 s20, s20, 4
	s_add_u32 s20, s20, s2
	s_lshl_b32 s19, s20, 6
	s_load_dwordx2 s[22:23], s[44:45], 0x168
	s_load_dwordx2 s[24:25], s[44:45], 0x170
	s_load_dwordx2 s[26:27], s[44:45], 0x68
	s_load_dwordx2 s[34:35], s[44:45], 0x70
	s_load_dwordx2 s[40:41], s[44:45], 0x180
	s_waitcnt lgkmcnt(0)
	s_lshl_b32 s20, s19, 3
	s_add_u32 s22, s22, s20
	s_addc_u32 s23, s23, 0
	s_lshl_b32 s20, s19, 7
	s_add_u32 s24, s24, s20
	s_addc_u32 s25, s25, 0
	s_lshl_b32 s20, s19, 6
	s_add_u32 s26, s26, s20
	s_addc_u32 s27, s27, 0
	s_add_u32 s34, s34, s20
	s_addc_u32 s35, s35, 0
	s_lshl_b32 s20, s1, 1
	s_add_u32 s20, s20, 1
	s_lshl_b32 s20, s20, 4
	s_add_u32 s20, s20, s2
	s_lshl_b32 s20, s20, 9
	s_add_u32 s40, s40, s20
	s_addc_u32 s41, s41, 0
	v_lshlrev_b32_e32 v38, 3, v32
	global_load_dwordx2 v[36:37], v38, s[22:23]
	global_load_dwordx2 v[54:55], v38, s[40:41]
	global_load_dwordx4 v[64:67], v40, s[24:25] offset:0
	global_load_dwordx4 v[68:71], v40, s[24:25] offset:16
	global_load_dwordx4 v[72:75], v40, s[24:25] offset:2048
	global_load_dwordx4 v[76:79], v40, s[24:25] offset:2064
	global_load_dwordx4 v[80:83], v41, s[24:25] offset:0
	global_load_dwordx4 v[84:87], v41, s[24:25] offset:16
	global_load_dwordx4 v[88:91], v41, s[24:25] offset:2048
	global_load_dwordx4 v[92:95], v41, s[24:25] offset:2064
	global_load_dwordx4 v[112:115], v49, s[26:27] offset:0
	global_load_dwordx4 v[116:119], v49, s[26:27] offset:16
	global_load_dwordx4 v[120:123], v49, s[26:27] offset:128
	global_load_dwordx4 v[124:127], v49, s[26:27] offset:144
	global_load_dwordx4 v[128:131], v49, s[34:35] offset:0
	global_load_dwordx4 v[132:135], v49, s[34:35] offset:16
	global_load_dwordx4 v[136:139], v49, s[34:35] offset:128
	global_load_dwordx4 v[140:143], v49, s[34:35] offset:144
	v_sub_u32_e32 v38, 63, v33
	v_lshlrev_b32_e32 v42, 10, v38
	v_lshl_add_u32 v42, v34, 4, v42
	s_mov_b32 s98, 0xffffc000
	global_load_dwordx4 v[96:99], v42, s[6:7]
	v_add_u32_e32 v42, s98, v42
	global_load_dwordx4 v[100:103], v42, s[6:7]
	v_add_u32_e32 v42, s98, v42
	global_load_dwordx4 v[104:107], v42, s[6:7]
	v_add_u32_e32 v42, s98, v42
	global_load_dwordx4 v[108:111], v42, s[6:7]
	s_waitcnt vmcnt(4)
	v_cvt_pk_bf16_f32 v168, v112, v113
	v_cvt_pk_bf16_f32 v169, v114, v115
	v_cvt_pk_bf16_f32 v170, v116, v117
	v_cvt_pk_bf16_f32 v171, v118, v119
	v_cvt_pk_bf16_f32 v172, v120, v121
	v_cvt_pk_bf16_f32 v173, v122, v123
	v_cvt_pk_bf16_f32 v174, v124, v125
	v_cvt_pk_bf16_f32 v175, v126, v127
	v_cvt_pk_bf16_f32 v176, v128, v129
	v_xor_b32_e32 v176, 0x80008000, v176
	v_cvt_pk_bf16_f32 v177, v130, v131
	v_xor_b32_e32 v177, 0x80008000, v177
	v_cvt_pk_bf16_f32 v178, v132, v133
	v_xor_b32_e32 v178, 0x80008000, v178
	v_cvt_pk_bf16_f32 v179, v134, v135
	v_xor_b32_e32 v179, 0x80008000, v179
	v_cvt_pk_bf16_f32 v180, v136, v137
	v_xor_b32_e32 v180, 0x80008000, v180
	v_cvt_pk_bf16_f32 v181, v138, v139
	v_xor_b32_e32 v181, 0x80008000, v181
	v_cvt_pk_bf16_f32 v182, v140, v141
	v_xor_b32_e32 v182, 0x80008000, v182
	v_cvt_pk_bf16_f32 v183, v142, v143
	v_xor_b32_e32 v183, 0x80008000, v183
	s_waitcnt vmcnt(3)
; __device__ void phase_s5_pass2(CParams& p, int l, int item, char* smem) {
;     ...
;     for (int s = 0; s < 4; s++) {
;       const int sb = dir == 0 ? s : 3 - s;
;       for (int i = 0; i < 16; i++) {
;         int tl = dir == 0 ? i : 15 - i;
;         int t = sb * 16 + tl;
;         float u[16];
; #pragma unroll
;         for (int k = 0; k < 4; k++) {
;           float4 uv = *(const float4*)(us + t * 16 + k * 4);
;           u[k * 4] = uv.x; u[k * 4 + 1] = uv.y; u[k * 4 + 2] = uv.z; u[k * 4 + 3] = uv.w;
;         }
;         f32x2 bu = {0.f, 0.f};
; #pragma unroll
;         for (int cc = 0; cc < 16; cc++) bu = __builtin_elementwise_fma(bb[cc], f32x2{u[cc], u[cc]}, bu);
;         float nr = A.x * hr - A.y * hi + bu[0];
;         float ni = A.x * hi + A.y * hr + bu[1];
;         hr = nr; hi = ni;
;         hs[tl * 136 + lane] = f2bf(hr);
;         hs[tl * 136 + 64 + lane] = f2bf(hi);
;       }
	v_mfma_f32_16x16x4_f32 v[0:3], v96, v64, 0
	v_mfma_f32_16x16x4_f32 v[4:7], v96, v65, 0
	v_mfma_f32_16x16x4_f32 v[8:11], v96, v72, 0
	v_mfma_f32_16x16x4_f32 v[12:15], v96, v73, 0
	v_mfma_f32_16x16x4_f32 v[16:19], v96, v80, 0
	v_mfma_f32_16x16x4_f32 v[20:23], v96, v81, 0
	v_mfma_f32_16x16x4_f32 v[24:27], v96, v88, 0
	v_mfma_f32_16x16x4_f32 v[28:31], v96, v89, 0
	v_mfma_f32_16x16x4_f32 v[0:3], v97, v66, v[0:3]
	v_mfma_f32_16x16x4_f32 v[4:7], v97, v67, v[4:7]
	v_mfma_f32_16x16x4_f32 v[8:11], v97, v74, v[8:11]
	v_mfma_f32_16x16x4_f32 v[12:15], v97, v75, v[12:15]
	v_mfma_f32_16x16x4_f32 v[16:19], v97, v82, v[16:19]
	v_mfma_f32_16x16x4_f32 v[20:23], v97, v83, v[20:23]
	v_mfma_f32_16x16x4_f32 v[24:27], v97, v90, v[24:27]
	v_mfma_f32_16x16x4_f32 v[28:31], v97, v91, v[28:31]
	v_mfma_f32_16x16x4_f32 v[0:3], v98, v68, v[0:3]
	v_mfma_f32_16x16x4_f32 v[4:7], v98, v69, v[4:7]
	v_mfma_f32_16x16x4_f32 v[8:11], v98, v76, v[8:11]
	v_mfma_f32_16x16x4_f32 v[12:15], v98, v77, v[12:15]
	v_mfma_f32_16x16x4_f32 v[16:19], v98, v84, v[16:19]
	v_mfma_f32_16x16x4_f32 v[20:23], v98, v85, v[20:23]
	v_mfma_f32_16x16x4_f32 v[24:27], v98, v92, v[24:27]
	v_mfma_f32_16x16x4_f32 v[28:31], v98, v93, v[28:31]
	v_mfma_f32_16x16x4_f32 v[0:3], v99, v70, v[0:3]
	v_mfma_f32_16x16x4_f32 v[4:7], v99, v71, v[4:7]
	v_mfma_f32_16x16x4_f32 v[8:11], v99, v78, v[8:11]
	v_mfma_f32_16x16x4_f32 v[12:15], v99, v79, v[12:15]
	v_mfma_f32_16x16x4_f32 v[16:19], v99, v86, v[16:19]
	v_mfma_f32_16x16x4_f32 v[20:23], v99, v87, v[20:23]
	v_mfma_f32_16x16x4_f32 v[24:27], v99, v94, v[24:27]
	v_mfma_f32_16x16x4_f32 v[28:31], v99, v95, v[28:31]
	s_nop 15
	s_nop 15
	ds_write2_b32 v44, v0, v4 offset0:0 offset1:1
	ds_write2_b32 v45, v1, v5 offset0:0 offset1:1
	ds_write2_b32 v46, v2, v6 offset0:0 offset1:1
	ds_write2_b32 v47, v3, v7 offset0:0 offset1:1
	ds_write2_b32 v44, v8, v12 offset0:32 offset1:33
	ds_write2_b32 v45, v9, v13 offset0:32 offset1:33
	ds_write2_b32 v46, v10, v14 offset0:32 offset1:33
	ds_write2_b32 v47, v11, v15 offset0:32 offset1:33
	ds_write2_b32 v44, v16, v20 offset0:64 offset1:65
	ds_write2_b32 v45, v17, v21 offset0:64 offset1:65
	ds_write2_b32 v46, v18, v22 offset0:64 offset1:65
	ds_write2_b32 v47, v19, v23 offset0:64 offset1:65
	ds_write2_b32 v44, v24, v28 offset0:96 offset1:97
	ds_write2_b32 v45, v25, v29 offset0:96 offset1:97
	ds_write2_b32 v46, v26, v30 offset0:96 offset1:97
	ds_write2_b32 v47, v27, v31 offset0:96 offset1:97
	ds_read_b64 v[0:1], v52 offset:0
	ds_read_b64 v[2:3], v52 offset:512
	ds_read_b64 v[4:5], v52 offset:1024
	ds_read_b64 v[6:7], v52 offset:1536
	ds_read_b64 v[8:9], v52 offset:2048
	ds_read_b64 v[10:11], v52 offset:2560
	ds_read_b64 v[12:13], v52 offset:3072
	ds_read_b64 v[14:15], v52 offset:3584
	ds_read_b64 v[16:17], v52 offset:4096
	ds_read_b64 v[18:19], v52 offset:4608
	ds_read_b64 v[20:21], v52 offset:5120
	ds_read_b64 v[22:23], v52 offset:5632
	ds_read_b64 v[24:25], v52 offset:6144
	ds_read_b64 v[26:27], v52 offset:6656
	ds_read_b64 v[28:29], v52 offset:7168
	ds_read_b64 v[30:31], v52 offset:7680
	s_waitcnt vmcnt(2)
	s_waitcnt lgkmcnt(15)
	v_fma_f32 v58, v36, v54, v0
	v_fma_f32 v59, v36, v55, v1
	v_mfma_f32_16x16x4_f32 v[112:115], v100, v64, 0
	v_mfma_f32_16x16x4_f32 v[116:119], v100, v65, 0
	v_fma_f32 v56, -v37, v55, v58
	v_fma_f32 v57, v37, v54, v59
	v_cvt_pk_bf16_f32 v62, v56, v57
	ds_write_b16 v60, v62 offset:4080
	ds_write_b16_d16_hi v60, v62 offset:4208
	s_waitcnt lgkmcnt(15)
	v_fma_f32 v58, v36, v56, v2
	v_fma_f32 v59, v36, v57, v3
	v_mfma_f32_16x16x4_f32 v[120:123], v100, v72, 0
	v_mfma_f32_16x16x4_f32 v[124:127], v100, v73, 0
	v_fma_f32 v54, -v37, v57, v58
	v_fma_f32 v55, v37, v56, v59
	v_cvt_pk_bf16_f32 v62, v54, v55
	ds_write_b16 v60, v62 offset:3808
	ds_write_b16_d16_hi v60, v62 offset:3936
	s_waitcnt lgkmcnt(15)
	v_fma_f32 v58, v36, v54, v4
	v_fma_f32 v59, v36, v55, v5
	v_mfma_f32_16x16x4_f32 v[128:131], v100, v80, 0
	v_mfma_f32_16x16x4_f32 v[132:135], v100, v81, 0
	v_fma_f32 v56, -v37, v55, v58
	v_fma_f32 v57, v37, v54, v59
	v_cvt_pk_bf16_f32 v62, v56, v57
	ds_write_b16 v60, v62 offset:3536
	ds_write_b16_d16_hi v60, v62 offset:3664
	s_waitcnt lgkmcnt(15)
	v_fma_f32 v58, v36, v56, v6
	v_fma_f32 v59, v36, v57, v7
	v_mfma_f32_16x16x4_f32 v[136:139], v100, v88, 0
	v_mfma_f32_16x16x4_f32 v[140:143], v100, v89, 0
	v_fma_f32 v54, -v37, v57, v58
	v_fma_f32 v55, v37, v56, v59
	v_cvt_pk_bf16_f32 v62, v54, v55
	ds_write_b16 v60, v62 offset:3264
	ds_write_b16_d16_hi v60, v62 offset:3392
	s_waitcnt lgkmcnt(15)
	v_fma_f32 v58, v36, v54, v8
	v_fma_f32 v59, v36, v55, v9
	v_mfma_f32_16x16x4_f32 v[112:115], v101, v66, v[112:115]
	v_mfma_f32_16x16x4_f32 v[116:119], v101, v67, v[116:119]
	v_fma_f32 v56, -v37, v55, v58
	v_fma_f32 v57, v37, v54, v59
	v_cvt_pk_bf16_f32 v62, v56, v57
	ds_write_b16 v60, v62 offset:2992
	ds_write_b16_d16_hi v60, v62 offset:3120
	s_waitcnt lgkmcnt(15)
	v_fma_f32 v58, v36, v56, v10
	v_fma_f32 v59, v36, v57, v11
	v_mfma_f32_16x16x4_f32 v[120:123], v101, v74, v[120:123]
	v_mfma_f32_16x16x4_f32 v[124:127], v101, v75, v[124:127]
	v_fma_f32 v54, -v37, v57, v58
	v_fma_f32 v55, v37, v56, v59
	v_cvt_pk_bf16_f32 v62, v54, v55
	ds_write_b16 v60, v62 offset:2720
	ds_write_b16_d16_hi v60, v62 offset:2848
	s_waitcnt lgkmcnt(15)
	v_fma_f32 v58, v36, v54, v12
	v_fma_f32 v59, v36, v55, v13
	v_mfma_f32_16x16x4_f32 v[128:131], v101, v82, v[128:131]
	v_mfma_f32_16x16x4_f32 v[132:135], v101, v83, v[132:135]
	v_fma_f32 v56, -v37, v55, v58
	v_fma_f32 v57, v37, v54, v59
	v_cvt_pk_bf16_f32 v62, v56, v57
	ds_write_b16 v60, v62 offset:2448
	ds_write_b16_d16_hi v60, v62 offset:2576
	s_waitcnt lgkmcnt(15)
; __device__ void phase_s5_pass2(CParams& p, int l, int item, char* smem) {
;     ...
;     for (int s = 0; s < 4; s++) {
;       const int sb = dir == 0 ? s : 3 - s;
;       for (int i = 0; i < 16; i++) {
;         int tl = dir == 0 ? i : 15 - i;
;         int t = sb * 16 + tl;
;         float u[16];
; #pragma unroll
;         for (int k = 0; k < 4; k++) {
;           float4 uv = *(const float4*)(us + t * 16 + k * 4);
;           u[k * 4] = uv.x; u[k * 4 + 1] = uv.y; u[k * 4 + 2] = uv.z; u[k * 4 + 3] = uv.w;
;         }
;         f32x2 bu = {0.f, 0.f};
; #pragma unroll
;         for (int cc = 0; cc < 16; cc++) bu = __builtin_elementwise_fma(bb[cc], f32x2{u[cc], u[cc]}, bu);
;         float nr = A.x * hr - A.y * hi + bu[0];
;         float ni = A.x * hi + A.y * hr + bu[1];
;         hr = nr; hi = ni;
;         hs[tl * 136 + lane] = f2bf(hr);
;         hs[tl * 136 + 64 + lane] = f2bf(hi);
;       }
;       __syncthreads();
; #pragma unroll
;       for (int ks = 0; ks < 4; ks++) {
;         bf16x8 a = *(const bf16x8*)(hs + l15 * 136 + ks * 32 + lq * 8);
;         acc[sb] = __builtin_amdgcn_mfma_f32_16x16x32_bf16(a, cf[ks], acc[sb], 0, 0, 0);
;       }
	v_fma_f32 v58, v36, v56, v14
	v_fma_f32 v59, v36, v57, v15
	v_mfma_f32_16x16x4_f32 v[136:139], v101, v90, v[136:139]
	v_mfma_f32_16x16x4_f32 v[140:143], v101, v91, v[140:143]
	v_fma_f32 v54, -v37, v57, v58
	v_fma_f32 v55, v37, v56, v59
	v_cvt_pk_bf16_f32 v62, v54, v55
	ds_write_b16 v60, v62 offset:2176
	ds_write_b16_d16_hi v60, v62 offset:2304
	s_waitcnt lgkmcnt(15)
	v_fma_f32 v58, v36, v54, v16
	v_fma_f32 v59, v36, v55, v17
	v_mfma_f32_16x16x4_f32 v[112:115], v102, v68, v[112:115]
	v_mfma_f32_16x16x4_f32 v[116:119], v102, v69, v[116:119]
	v_fma_f32 v56, -v37, v55, v58
	v_fma_f32 v57, v37, v54, v59
	v_cvt_pk_bf16_f32 v62, v56, v57
	ds_write_b16 v60, v62 offset:1904
	ds_write_b16_d16_hi v60, v62 offset:2032
	s_waitcnt lgkmcnt(15)
	v_fma_f32 v58, v36, v56, v18
	v_fma_f32 v59, v36, v57, v19
	v_mfma_f32_16x16x4_f32 v[120:123], v102, v76, v[120:123]
	v_mfma_f32_16x16x4_f32 v[124:127], v102, v77, v[124:127]
	v_fma_f32 v54, -v37, v57, v58
	v_fma_f32 v55, v37, v56, v59
	v_cvt_pk_bf16_f32 v62, v54, v55
	ds_write_b16 v60, v62 offset:1632
	ds_write_b16_d16_hi v60, v62 offset:1760
	s_waitcnt lgkmcnt(15)
	v_fma_f32 v58, v36, v54, v20
	v_fma_f32 v59, v36, v55, v21
	v_mfma_f32_16x16x4_f32 v[128:131], v102, v84, v[128:131]
	v_mfma_f32_16x16x4_f32 v[132:135], v102, v85, v[132:135]
	v_fma_f32 v56, -v37, v55, v58
	v_fma_f32 v57, v37, v54, v59
	v_cvt_pk_bf16_f32 v62, v56, v57
	ds_write_b16 v60, v62 offset:1360
	ds_write_b16_d16_hi v60, v62 offset:1488
	s_waitcnt lgkmcnt(15)
	v_fma_f32 v58, v36, v56, v22
	v_fma_f32 v59, v36, v57, v23
	v_mfma_f32_16x16x4_f32 v[136:139], v102, v92, v[136:139]
	v_mfma_f32_16x16x4_f32 v[140:143], v102, v93, v[140:143]
	v_fma_f32 v54, -v37, v57, v58
	v_fma_f32 v55, v37, v56, v59
	v_cvt_pk_bf16_f32 v62, v54, v55
	ds_write_b16 v60, v62 offset:1088
	ds_write_b16_d16_hi v60, v62 offset:1216
	s_waitcnt lgkmcnt(15)
	v_fma_f32 v58, v36, v54, v24
	v_fma_f32 v59, v36, v55, v25
	v_mfma_f32_16x16x4_f32 v[112:115], v103, v70, v[112:115]
	v_mfma_f32_16x16x4_f32 v[116:119], v103, v71, v[116:119]
	v_fma_f32 v56, -v37, v55, v58
	v_fma_f32 v57, v37, v54, v59
	v_cvt_pk_bf16_f32 v62, v56, v57
	ds_write_b16 v60, v62 offset:816
	ds_write_b16_d16_hi v60, v62 offset:944
	s_waitcnt lgkmcnt(15)
	v_fma_f32 v58, v36, v56, v26
	v_fma_f32 v59, v36, v57, v27
	v_mfma_f32_16x16x4_f32 v[120:123], v103, v78, v[120:123]
	v_mfma_f32_16x16x4_f32 v[124:127], v103, v79, v[124:127]
	v_fma_f32 v54, -v37, v57, v58
	v_fma_f32 v55, v37, v56, v59
	v_cvt_pk_bf16_f32 v62, v54, v55
	ds_write_b16 v60, v62 offset:544
	ds_write_b16_d16_hi v60, v62 offset:672
	s_waitcnt lgkmcnt(15)
	v_fma_f32 v58, v36, v54, v28
	v_fma_f32 v59, v36, v55, v29
	v_mfma_f32_16x16x4_f32 v[128:131], v103, v86, v[128:131]
	v_mfma_f32_16x16x4_f32 v[132:135], v103, v87, v[132:135]
	v_fma_f32 v56, -v37, v55, v58
	v_fma_f32 v57, v37, v54, v59
	v_cvt_pk_bf16_f32 v62, v56, v57
	ds_write_b16 v60, v62 offset:272
	ds_write_b16_d16_hi v60, v62 offset:400
	s_waitcnt lgkmcnt(15)
	v_fma_f32 v58, v36, v56, v30
	v_fma_f32 v59, v36, v57, v31
	v_mfma_f32_16x16x4_f32 v[136:139], v103, v94, v[136:139]
	v_mfma_f32_16x16x4_f32 v[140:143], v103, v95, v[140:143]
	v_fma_f32 v54, -v37, v57, v58
	v_fma_f32 v55, v37, v56, v59
	v_cvt_pk_bf16_f32 v62, v54, v55
	ds_write_b16 v60, v62 offset:0
	ds_write_b16_d16_hi v60, v62 offset:128
	ds_read_b128 v[184:187], v61 offset:0
	ds_read_b128 v[188:191], v61 offset:64
	ds_read_b128 v[192:195], v61 offset:128
	ds_read_b128 v[196:199], v61 offset:192
	s_waitcnt lgkmcnt(0)
	v_mfma_f32_16x16x32_bf16 v[160:163], v[184:187], v[168:171], v[160:163]
	v_mfma_f32_16x16x32_bf16 v[160:163], v[188:191], v[172:175], v[160:163]
	v_mfma_f32_16x16x32_bf16 v[160:163], v[192:195], v[176:179], v[160:163]
	v_mfma_f32_16x16x32_bf16 v[160:163], v[196:199], v[180:183], v[160:163]
	s_nop 15
	s_nop 15
	ds_write2_b32 v44, v112, v116 offset0:0 offset1:1
	ds_write2_b32 v45, v113, v117 offset0:0 offset1:1
	ds_write2_b32 v46, v114, v118 offset0:0 offset1:1
	ds_write2_b32 v47, v115, v119 offset0:0 offset1:1
	ds_write2_b32 v44, v120, v124 offset0:32 offset1:33
	ds_write2_b32 v45, v121, v125 offset0:32 offset1:33
	ds_write2_b32 v46, v122, v126 offset0:32 offset1:33
	ds_write2_b32 v47, v123, v127 offset0:32 offset1:33
	ds_write2_b32 v44, v128, v132 offset0:64 offset1:65
	ds_write2_b32 v45, v129, v133 offset0:64 offset1:65
	ds_write2_b32 v46, v130, v134 offset0:64 offset1:65
	ds_write2_b32 v47, v131, v135 offset0:64 offset1:65
	ds_write2_b32 v44, v136, v140 offset0:96 offset1:97
	ds_write2_b32 v45, v137, v141 offset0:96 offset1:97
	ds_write2_b32 v46, v138, v142 offset0:96 offset1:97
	ds_write2_b32 v47, v139, v143 offset0:96 offset1:97
	ds_read_b64 v[112:113], v52 offset:0
	ds_read_b64 v[114:115], v52 offset:512
	ds_read_b64 v[116:117], v52 offset:1024
	ds_read_b64 v[118:119], v52 offset:1536
	ds_read_b64 v[120:121], v52 offset:2048
	ds_read_b64 v[122:123], v52 offset:2560
	ds_read_b64 v[124:125], v52 offset:3072
	ds_read_b64 v[126:127], v52 offset:3584
	ds_read_b64 v[128:129], v52 offset:4096
	ds_read_b64 v[130:131], v52 offset:4608
	ds_read_b64 v[132:133], v52 offset:5120
	ds_read_b64 v[134:135], v52 offset:5632
	ds_read_b64 v[136:137], v52 offset:6144
	ds_read_b64 v[138:139], v52 offset:6656
	ds_read_b64 v[140:141], v52 offset:7168
	ds_read_b64 v[142:143], v52 offset:7680
	s_waitcnt vmcnt(1)
	s_waitcnt lgkmcnt(15)
	v_fma_f32 v58, v36, v54, v112
	v_fma_f32 v59, v36, v55, v113
	v_mfma_f32_16x16x4_f32 v[0:3], v104, v64, 0
	v_mfma_f32_16x16x4_f32 v[4:7], v104, v65, 0
	v_fma_f32 v56, -v37, v55, v58
	v_fma_f32 v57, v37, v54, v59
	v_cvt_pk_bf16_f32 v62, v56, v57
	ds_write_b16 v60, v62 offset:4080
	ds_write_b16_d16_hi v60, v62 offset:4208
	s_waitcnt lgkmcnt(15)
; __device__ void phase_s5_pass2(CParams& p, int l, int item, char* smem) {
;     ...
;     for (int s = 0; s < 4; s++) {
;       const int sb = dir == 0 ? s : 3 - s;
;       for (int i = 0; i < 16; i++) {
;         int tl = dir == 0 ? i : 15 - i;
;         int t = sb * 16 + tl;
;         float u[16];
; #pragma unroll
;         for (int k = 0; k < 4; k++) {
;           float4 uv = *(const float4*)(us + t * 16 + k * 4);
;           u[k * 4] = uv.x; u[k * 4 + 1] = uv.y; u[k * 4 + 2] = uv.z; u[k * 4 + 3] = uv.w;
;         }
;         f32x2 bu = {0.f, 0.f};
; #pragma unroll
;         for (int cc = 0; cc < 16; cc++) bu = __builtin_elementwise_fma(bb[cc], f32x2{u[cc], u[cc]}, bu);
;         float nr = A.x * hr - A.y * hi + bu[0];
;         float ni = A.x * hi + A.y * hr + bu[1];
;         hr = nr; hi = ni;
;         hs[tl * 136 + lane] = f2bf(hr);
;         hs[tl * 136 + 64 + lane] = f2bf(hi);
;       }
	v_fma_f32 v58, v36, v56, v114
	v_fma_f32 v59, v36, v57, v115
	v_mfma_f32_16x16x4_f32 v[8:11], v104, v72, 0
	v_mfma_f32_16x16x4_f32 v[12:15], v104, v73, 0
	v_fma_f32 v54, -v37, v57, v58
	v_fma_f32 v55, v37, v56, v59
	v_cvt_pk_bf16_f32 v62, v54, v55
	ds_write_b16 v60, v62 offset:3808
	ds_write_b16_d16_hi v60, v62 offset:3936
	s_waitcnt lgkmcnt(15)
	v_fma_f32 v58, v36, v54, v116
	v_fma_f32 v59, v36, v55, v117
	v_mfma_f32_16x16x4_f32 v[16:19], v104, v80, 0
	v_mfma_f32_16x16x4_f32 v[20:23], v104, v81, 0
	v_fma_f32 v56, -v37, v55, v58
	v_fma_f32 v57, v37, v54, v59
	v_cvt_pk_bf16_f32 v62, v56, v57
	ds_write_b16 v60, v62 offset:3536
	ds_write_b16_d16_hi v60, v62 offset:3664
	s_waitcnt lgkmcnt(15)
	v_fma_f32 v58, v36, v56, v118
	v_fma_f32 v59, v36, v57, v119
	v_mfma_f32_16x16x4_f32 v[24:27], v104, v88, 0
	v_mfma_f32_16x16x4_f32 v[28:31], v104, v89, 0
	v_fma_f32 v54, -v37, v57, v58
	v_fma_f32 v55, v37, v56, v59
	v_cvt_pk_bf16_f32 v62, v54, v55
	ds_write_b16 v60, v62 offset:3264
	ds_write_b16_d16_hi v60, v62 offset:3392
	s_waitcnt lgkmcnt(15)
	v_fma_f32 v58, v36, v54, v120
	v_fma_f32 v59, v36, v55, v121
	v_mfma_f32_16x16x4_f32 v[0:3], v105, v66, v[0:3]
	v_mfma_f32_16x16x4_f32 v[4:7], v105, v67, v[4:7]
	v_fma_f32 v56, -v37, v55, v58
	v_fma_f32 v57, v37, v54, v59
	v_cvt_pk_bf16_f32 v62, v56, v57
	ds_write_b16 v60, v62 offset:2992
	ds_write_b16_d16_hi v60, v62 offset:3120
	s_waitcnt lgkmcnt(15)
	v_fma_f32 v58, v36, v56, v122
	v_fma_f32 v59, v36, v57, v123
	v_mfma_f32_16x16x4_f32 v[8:11], v105, v74, v[8:11]
	v_mfma_f32_16x16x4_f32 v[12:15], v105, v75, v[12:15]
	v_fma_f32 v54, -v37, v57, v58
	v_fma_f32 v55, v37, v56, v59
	v_cvt_pk_bf16_f32 v62, v54, v55
	ds_write_b16 v60, v62 offset:2720
	ds_write_b16_d16_hi v60, v62 offset:2848
	s_waitcnt lgkmcnt(15)
	v_fma_f32 v58, v36, v54, v124
	v_fma_f32 v59, v36, v55, v125
	v_mfma_f32_16x16x4_f32 v[16:19], v105, v82, v[16:19]
	v_mfma_f32_16x16x4_f32 v[20:23], v105, v83, v[20:23]
	v_fma_f32 v56, -v37, v55, v58
	v_fma_f32 v57, v37, v54, v59
	v_cvt_pk_bf16_f32 v62, v56, v57
	ds_write_b16 v60, v62 offset:2448
	ds_write_b16_d16_hi v60, v62 offset:2576
	s_waitcnt lgkmcnt(15)
	v_fma_f32 v58, v36, v56, v126
	v_fma_f32 v59, v36, v57, v127
	v_mfma_f32_16x16x4_f32 v[24:27], v105, v90, v[24:27]
	v_mfma_f32_16x16x4_f32 v[28:31], v105, v91, v[28:31]
	v_fma_f32 v54, -v37, v57, v58
	v_fma_f32 v55, v37, v56, v59
	v_cvt_pk_bf16_f32 v62, v54, v55
	ds_write_b16 v60, v62 offset:2176
	ds_write_b16_d16_hi v60, v62 offset:2304
	s_waitcnt lgkmcnt(15)
	v_fma_f32 v58, v36, v54, v128
	v_fma_f32 v59, v36, v55, v129
	v_mfma_f32_16x16x4_f32 v[0:3], v106, v68, v[0:3]
	v_mfma_f32_16x16x4_f32 v[4:7], v106, v69, v[4:7]
	v_fma_f32 v56, -v37, v55, v58
	v_fma_f32 v57, v37, v54, v59
	v_cvt_pk_bf16_f32 v62, v56, v57
	ds_write_b16 v60, v62 offset:1904
	ds_write_b16_d16_hi v60, v62 offset:2032
	s_waitcnt lgkmcnt(15)
	v_fma_f32 v58, v36, v56, v130
	v_fma_f32 v59, v36, v57, v131
	v_mfma_f32_16x16x4_f32 v[8:11], v106, v76, v[8:11]
	v_mfma_f32_16x16x4_f32 v[12:15], v106, v77, v[12:15]
	v_fma_f32 v54, -v37, v57, v58
	v_fma_f32 v55, v37, v56, v59
	v_cvt_pk_bf16_f32 v62, v54, v55
	ds_write_b16 v60, v62 offset:1632
	ds_write_b16_d16_hi v60, v62 offset:1760
	s_waitcnt lgkmcnt(15)
	v_fma_f32 v58, v36, v54, v132
	v_fma_f32 v59, v36, v55, v133
	v_mfma_f32_16x16x4_f32 v[16:19], v106, v84, v[16:19]
	v_mfma_f32_16x16x4_f32 v[20:23], v106, v85, v[20:23]
	v_fma_f32 v56, -v37, v55, v58
	v_fma_f32 v57, v37, v54, v59
	v_cvt_pk_bf16_f32 v62, v56, v57
	ds_write_b16 v60, v62 offset:1360
	ds_write_b16_d16_hi v60, v62 offset:1488
	s_waitcnt lgkmcnt(15)
	v_fma_f32 v58, v36, v56, v134
	v_fma_f32 v59, v36, v57, v135
	v_mfma_f32_16x16x4_f32 v[24:27], v106, v92, v[24:27]
	v_mfma_f32_16x16x4_f32 v[28:31], v106, v93, v[28:31]
	v_fma_f32 v54, -v37, v57, v58
	v_fma_f32 v55, v37, v56, v59
	v_cvt_pk_bf16_f32 v62, v54, v55
	ds_write_b16 v60, v62 offset:1088
	ds_write_b16_d16_hi v60, v62 offset:1216
	s_waitcnt lgkmcnt(15)
	v_fma_f32 v58, v36, v54, v136
	v_fma_f32 v59, v36, v55, v137
	v_mfma_f32_16x16x4_f32 v[0:3], v107, v70, v[0:3]
	v_mfma_f32_16x16x4_f32 v[4:7], v107, v71, v[4:7]
	v_fma_f32 v56, -v37, v55, v58
	v_fma_f32 v57, v37, v54, v59
	v_cvt_pk_bf16_f32 v62, v56, v57
	ds_write_b16 v60, v62 offset:816
	ds_write_b16_d16_hi v60, v62 offset:944
	s_waitcnt lgkmcnt(15)
	v_fma_f32 v58, v36, v56, v138
	v_fma_f32 v59, v36, v57, v139
	v_mfma_f32_16x16x4_f32 v[8:11], v107, v78, v[8:11]
	v_mfma_f32_16x16x4_f32 v[12:15], v107, v79, v[12:15]
	v_fma_f32 v54, -v37, v57, v58
	v_fma_f32 v55, v37, v56, v59
	v_cvt_pk_bf16_f32 v62, v54, v55
	ds_write_b16 v60, v62 offset:544
	ds_write_b16_d16_hi v60, v62 offset:672
	s_waitcnt lgkmcnt(15)
	v_fma_f32 v58, v36, v54, v140
	v_fma_f32 v59, v36, v55, v141
	v_mfma_f32_16x16x4_f32 v[16:19], v107, v86, v[16:19]
	v_mfma_f32_16x16x4_f32 v[20:23], v107, v87, v[20:23]
	v_fma_f32 v56, -v37, v55, v58
	v_fma_f32 v57, v37, v54, v59
	v_cvt_pk_bf16_f32 v62, v56, v57
	ds_write_b16 v60, v62 offset:272
	ds_write_b16_d16_hi v60, v62 offset:400
	s_waitcnt lgkmcnt(15)
	v_fma_f32 v58, v36, v56, v142
	v_fma_f32 v59, v36, v57, v143
	v_mfma_f32_16x16x4_f32 v[24:27], v107, v94, v[24:27]
	v_mfma_f32_16x16x4_f32 v[28:31], v107, v95, v[28:31]
	v_fma_f32 v54, -v37, v57, v58
	v_fma_f32 v55, v37, v56, v59
	v_cvt_pk_bf16_f32 v62, v54, v55
	ds_write_b16 v60, v62 offset:0
	ds_write_b16_d16_hi v60, v62 offset:128
	ds_read_b128 v[184:187], v61 offset:0
	ds_read_b128 v[188:191], v61 offset:64
	ds_read_b128 v[192:195], v61 offset:128
	ds_read_b128 v[196:199], v61 offset:192
	s_waitcnt lgkmcnt(0)
; __device__ void phase_s5_pass2(CParams& p, int l, int item, char* smem) {
;     ...
;       for (int i = 0; i < 16; i++) {
;         int tl = dir == 0 ? i : 15 - i;
;         int t = sb * 16 + tl;
;         float u[16];
; #pragma unroll
;         for (int k = 0; k < 4; k++) {
;           float4 uv = *(const float4*)(us + t * 16 + k * 4);
;           u[k * 4] = uv.x; u[k * 4 + 1] = uv.y; u[k * 4 + 2] = uv.z; u[k * 4 + 3] = uv.w;
;         }
;         f32x2 bu = {0.f, 0.f};
; #pragma unroll
;         for (int cc = 0; cc < 16; cc++) bu = __builtin_elementwise_fma(bb[cc], f32x2{u[cc], u[cc]}, bu);
;         float nr = A.x * hr - A.y * hi + bu[0];
;         float ni = A.x * hi + A.y * hr + bu[1];
;         hr = nr; hi = ni;
;         hs[tl * 136 + lane] = f2bf(hr);
;         hs[tl * 136 + 64 + lane] = f2bf(hi);
;       }
;       __syncthreads();
; #pragma unroll
;       for (int ks = 0; ks < 4; ks++) {
;         bf16x8 a = *(const bf16x8*)(hs + l15 * 136 + ks * 32 + lq * 8);
;         acc[sb] = __builtin_amdgcn_mfma_f32_16x16x32_bf16(a, cf[ks], acc[sb], 0, 0, 0);
;       }
	v_mfma_f32_16x16x32_bf16 v[156:159], v[184:187], v[168:171], v[156:159]
	v_mfma_f32_16x16x32_bf16 v[156:159], v[188:191], v[172:175], v[156:159]
	v_mfma_f32_16x16x32_bf16 v[156:159], v[192:195], v[176:179], v[156:159]
	v_mfma_f32_16x16x32_bf16 v[156:159], v[196:199], v[180:183], v[156:159]
	s_nop 15
	s_nop 15
	ds_write2_b32 v44, v0, v4 offset0:0 offset1:1
	ds_write2_b32 v45, v1, v5 offset0:0 offset1:1
	ds_write2_b32 v46, v2, v6 offset0:0 offset1:1
	ds_write2_b32 v47, v3, v7 offset0:0 offset1:1
	ds_write2_b32 v44, v8, v12 offset0:32 offset1:33
	ds_write2_b32 v45, v9, v13 offset0:32 offset1:33
	ds_write2_b32 v46, v10, v14 offset0:32 offset1:33
	ds_write2_b32 v47, v11, v15 offset0:32 offset1:33
	ds_write2_b32 v44, v16, v20 offset0:64 offset1:65
	ds_write2_b32 v45, v17, v21 offset0:64 offset1:65
	ds_write2_b32 v46, v18, v22 offset0:64 offset1:65
	ds_write2_b32 v47, v19, v23 offset0:64 offset1:65
	ds_write2_b32 v44, v24, v28 offset0:96 offset1:97
	ds_write2_b32 v45, v25, v29 offset0:96 offset1:97
	ds_write2_b32 v46, v26, v30 offset0:96 offset1:97
	ds_write2_b32 v47, v27, v31 offset0:96 offset1:97
	ds_read_b64 v[0:1], v52 offset:0
	ds_read_b64 v[2:3], v52 offset:512
	ds_read_b64 v[4:5], v52 offset:1024
	ds_read_b64 v[6:7], v52 offset:1536
	ds_read_b64 v[8:9], v52 offset:2048
	ds_read_b64 v[10:11], v52 offset:2560
	ds_read_b64 v[12:13], v52 offset:3072
	ds_read_b64 v[14:15], v52 offset:3584
	ds_read_b64 v[16:17], v52 offset:4096
	ds_read_b64 v[18:19], v52 offset:4608
	ds_read_b64 v[20:21], v52 offset:5120
	ds_read_b64 v[22:23], v52 offset:5632
	ds_read_b64 v[24:25], v52 offset:6144
	ds_read_b64 v[26:27], v52 offset:6656
	ds_read_b64 v[28:29], v52 offset:7168
	ds_read_b64 v[30:31], v52 offset:7680
	s_waitcnt vmcnt(0)
	s_waitcnt lgkmcnt(15)
	v_fma_f32 v58, v36, v54, v0
	v_fma_f32 v59, v36, v55, v1
	v_mfma_f32_16x16x4_f32 v[112:115], v108, v64, 0
	v_mfma_f32_16x16x4_f32 v[116:119], v108, v65, 0
	v_fma_f32 v56, -v37, v55, v58
	v_fma_f32 v57, v37, v54, v59
	v_cvt_pk_bf16_f32 v62, v56, v57
	ds_write_b16 v60, v62 offset:4080
	ds_write_b16_d16_hi v60, v62 offset:4208
	s_waitcnt lgkmcnt(15)
	v_fma_f32 v58, v36, v56, v2
	v_fma_f32 v59, v36, v57, v3
	v_mfma_f32_16x16x4_f32 v[120:123], v108, v72, 0
	v_mfma_f32_16x16x4_f32 v[124:127], v108, v73, 0
	v_fma_f32 v54, -v37, v57, v58
	v_fma_f32 v55, v37, v56, v59
	v_cvt_pk_bf16_f32 v62, v54, v55
	ds_write_b16 v60, v62 offset:3808
	ds_write_b16_d16_hi v60, v62 offset:3936
	s_waitcnt lgkmcnt(15)
	v_fma_f32 v58, v36, v54, v4
	v_fma_f32 v59, v36, v55, v5
	v_mfma_f32_16x16x4_f32 v[128:131], v108, v80, 0
	v_mfma_f32_16x16x4_f32 v[132:135], v108, v81, 0
	v_fma_f32 v56, -v37, v55, v58
	v_fma_f32 v57, v37, v54, v59
	v_cvt_pk_bf16_f32 v62, v56, v57
	ds_write_b16 v60, v62 offset:3536
	ds_write_b16_d16_hi v60, v62 offset:3664
	s_waitcnt lgkmcnt(15)
	v_fma_f32 v58, v36, v56, v6
	v_fma_f32 v59, v36, v57, v7
	v_mfma_f32_16x16x4_f32 v[136:139], v108, v88, 0
	v_mfma_f32_16x16x4_f32 v[140:143], v108, v89, 0
	v_fma_f32 v54, -v37, v57, v58
	v_fma_f32 v55, v37, v56, v59
	v_cvt_pk_bf16_f32 v62, v54, v55
	ds_write_b16 v60, v62 offset:3264
	ds_write_b16_d16_hi v60, v62 offset:3392
	s_waitcnt lgkmcnt(15)
	v_fma_f32 v58, v36, v54, v8
	v_fma_f32 v59, v36, v55, v9
	v_mfma_f32_16x16x4_f32 v[112:115], v109, v66, v[112:115]
	v_mfma_f32_16x16x4_f32 v[116:119], v109, v67, v[116:119]
	v_fma_f32 v56, -v37, v55, v58
	v_fma_f32 v57, v37, v54, v59
	v_cvt_pk_bf16_f32 v62, v56, v57
	ds_write_b16 v60, v62 offset:2992
	ds_write_b16_d16_hi v60, v62 offset:3120
	s_waitcnt lgkmcnt(15)
	v_fma_f32 v58, v36, v56, v10
	v_fma_f32 v59, v36, v57, v11
	v_mfma_f32_16x16x4_f32 v[120:123], v109, v74, v[120:123]
	v_mfma_f32_16x16x4_f32 v[124:127], v109, v75, v[124:127]
	v_fma_f32 v54, -v37, v57, v58
	v_fma_f32 v55, v37, v56, v59
	v_cvt_pk_bf16_f32 v62, v54, v55
	ds_write_b16 v60, v62 offset:2720
	ds_write_b16_d16_hi v60, v62 offset:2848
	s_waitcnt lgkmcnt(15)
	v_fma_f32 v58, v36, v54, v12
	v_fma_f32 v59, v36, v55, v13
	v_mfma_f32_16x16x4_f32 v[128:131], v109, v82, v[128:131]
	v_mfma_f32_16x16x4_f32 v[132:135], v109, v83, v[132:135]
	v_fma_f32 v56, -v37, v55, v58
	v_fma_f32 v57, v37, v54, v59
	v_cvt_pk_bf16_f32 v62, v56, v57
	ds_write_b16 v60, v62 offset:2448
	ds_write_b16_d16_hi v60, v62 offset:2576
	s_waitcnt lgkmcnt(15)
	v_fma_f32 v58, v36, v56, v14
	v_fma_f32 v59, v36, v57, v15
	v_mfma_f32_16x16x4_f32 v[136:139], v109, v90, v[136:139]
	v_mfma_f32_16x16x4_f32 v[140:143], v109, v91, v[140:143]
	v_fma_f32 v54, -v37, v57, v58
	v_fma_f32 v55, v37, v56, v59
	v_cvt_pk_bf16_f32 v62, v54, v55
	ds_write_b16 v60, v62 offset:2176
	ds_write_b16_d16_hi v60, v62 offset:2304
	s_waitcnt lgkmcnt(15)
	v_fma_f32 v58, v36, v54, v16
	v_fma_f32 v59, v36, v55, v17
	v_mfma_f32_16x16x4_f32 v[112:115], v110, v68, v[112:115]
	v_mfma_f32_16x16x4_f32 v[116:119], v110, v69, v[116:119]
	v_fma_f32 v56, -v37, v55, v58
	v_fma_f32 v57, v37, v54, v59
	v_cvt_pk_bf16_f32 v62, v56, v57
	ds_write_b16 v60, v62 offset:1904
	ds_write_b16_d16_hi v60, v62 offset:2032
	s_waitcnt lgkmcnt(15)
	v_fma_f32 v58, v36, v56, v18
	v_fma_f32 v59, v36, v57, v19
	v_mfma_f32_16x16x4_f32 v[120:123], v110, v76, v[120:123]
	v_mfma_f32_16x16x4_f32 v[124:127], v110, v77, v[124:127]
	v_fma_f32 v54, -v37, v57, v58
	v_fma_f32 v55, v37, v56, v59
	v_cvt_pk_bf16_f32 v62, v54, v55
	ds_write_b16 v60, v62 offset:1632
	ds_write_b16_d16_hi v60, v62 offset:1760
	s_waitcnt lgkmcnt(15)
	v_fma_f32 v58, v36, v54, v20
	v_fma_f32 v59, v36, v55, v21
	v_mfma_f32_16x16x4_f32 v[128:131], v110, v84, v[128:131]
	v_mfma_f32_16x16x4_f32 v[132:135], v110, v85, v[132:135]
	v_fma_f32 v56, -v37, v55, v58
	v_fma_f32 v57, v37, v54, v59
	v_cvt_pk_bf16_f32 v62, v56, v57
	ds_write_b16 v60, v62 offset:1360
	ds_write_b16_d16_hi v60, v62 offset:1488
	s_waitcnt lgkmcnt(15)
; __device__ void phase_s5_pass2(CParams& p, int l, int item, char* smem) {
;     ...
;     for (int s = 0; s < 4; s++) {
;       const int sb = dir == 0 ? s : 3 - s;
;       for (int i = 0; i < 16; i++) {
;         int tl = dir == 0 ? i : 15 - i;
;         int t = sb * 16 + tl;
;         float u[16];
; #pragma unroll
;         for (int k = 0; k < 4; k++) {
;           float4 uv = *(const float4*)(us + t * 16 + k * 4);
;           u[k * 4] = uv.x; u[k * 4 + 1] = uv.y; u[k * 4 + 2] = uv.z; u[k * 4 + 3] = uv.w;
;         }
;         f32x2 bu = {0.f, 0.f};
; #pragma unroll
;         for (int cc = 0; cc < 16; cc++) bu = __builtin_elementwise_fma(bb[cc], f32x2{u[cc], u[cc]}, bu);
;         float nr = A.x * hr - A.y * hi + bu[0];
;         float ni = A.x * hi + A.y * hr + bu[1];
;         hr = nr; hi = ni;
;         hs[tl * 136 + lane] = f2bf(hr);
;         hs[tl * 136 + 64 + lane] = f2bf(hi);
;       }
;       __syncthreads();
; #pragma unroll
;       for (int ks = 0; ks < 4; ks++) {
;         bf16x8 a = *(const bf16x8*)(hs + l15 * 136 + ks * 32 + lq * 8);
;         acc[sb] = __builtin_amdgcn_mfma_f32_16x16x32_bf16(a, cf[ks], acc[sb], 0, 0, 0);
;       }
	v_fma_f32 v58, v36, v56, v22
	v_fma_f32 v59, v36, v57, v23
	v_mfma_f32_16x16x4_f32 v[136:139], v110, v92, v[136:139]
	v_mfma_f32_16x16x4_f32 v[140:143], v110, v93, v[140:143]
	v_fma_f32 v54, -v37, v57, v58
	v_fma_f32 v55, v37, v56, v59
	v_cvt_pk_bf16_f32 v62, v54, v55
	ds_write_b16 v60, v62 offset:1088
	ds_write_b16_d16_hi v60, v62 offset:1216
	s_waitcnt lgkmcnt(15)
	v_fma_f32 v58, v36, v54, v24
	v_fma_f32 v59, v36, v55, v25
	v_mfma_f32_16x16x4_f32 v[112:115], v111, v70, v[112:115]
	v_mfma_f32_16x16x4_f32 v[116:119], v111, v71, v[116:119]
	v_fma_f32 v56, -v37, v55, v58
	v_fma_f32 v57, v37, v54, v59
	v_cvt_pk_bf16_f32 v62, v56, v57
	ds_write_b16 v60, v62 offset:816
	ds_write_b16_d16_hi v60, v62 offset:944
	s_waitcnt lgkmcnt(15)
	v_fma_f32 v58, v36, v56, v26
	v_fma_f32 v59, v36, v57, v27
	v_mfma_f32_16x16x4_f32 v[120:123], v111, v78, v[120:123]
	v_mfma_f32_16x16x4_f32 v[124:127], v111, v79, v[124:127]
	v_fma_f32 v54, -v37, v57, v58
	v_fma_f32 v55, v37, v56, v59
	v_cvt_pk_bf16_f32 v62, v54, v55
	ds_write_b16 v60, v62 offset:544
	ds_write_b16_d16_hi v60, v62 offset:672
	s_waitcnt lgkmcnt(15)
	v_fma_f32 v58, v36, v54, v28
	v_fma_f32 v59, v36, v55, v29
	v_mfma_f32_16x16x4_f32 v[128:131], v111, v86, v[128:131]
	v_mfma_f32_16x16x4_f32 v[132:135], v111, v87, v[132:135]
	v_fma_f32 v56, -v37, v55, v58
	v_fma_f32 v57, v37, v54, v59
	v_cvt_pk_bf16_f32 v62, v56, v57
	ds_write_b16 v60, v62 offset:272
	ds_write_b16_d16_hi v60, v62 offset:400
	s_waitcnt lgkmcnt(15)
	v_fma_f32 v58, v36, v56, v30
	v_fma_f32 v59, v36, v57, v31
	v_mfma_f32_16x16x4_f32 v[136:139], v111, v94, v[136:139]
	v_mfma_f32_16x16x4_f32 v[140:143], v111, v95, v[140:143]
	v_fma_f32 v54, -v37, v57, v58
	v_fma_f32 v55, v37, v56, v59
	v_cvt_pk_bf16_f32 v62, v54, v55
	ds_write_b16 v60, v62 offset:0
	ds_write_b16_d16_hi v60, v62 offset:128
	ds_read_b128 v[184:187], v61 offset:0
	ds_read_b128 v[188:191], v61 offset:64
	ds_read_b128 v[192:195], v61 offset:128
	ds_read_b128 v[196:199], v61 offset:192
	s_waitcnt lgkmcnt(0)
	v_mfma_f32_16x16x32_bf16 v[152:155], v[184:187], v[168:171], v[152:155]
	v_mfma_f32_16x16x32_bf16 v[152:155], v[188:191], v[172:175], v[152:155]
	v_mfma_f32_16x16x32_bf16 v[152:155], v[192:195], v[176:179], v[152:155]
	v_mfma_f32_16x16x32_bf16 v[152:155], v[196:199], v[180:183], v[152:155]
	s_nop 15
	s_nop 15
	ds_write2_b32 v44, v112, v116 offset0:0 offset1:1
	ds_write2_b32 v45, v113, v117 offset0:0 offset1:1
	ds_write2_b32 v46, v114, v118 offset0:0 offset1:1
	ds_write2_b32 v47, v115, v119 offset0:0 offset1:1
	ds_write2_b32 v44, v120, v124 offset0:32 offset1:33
	ds_write2_b32 v45, v121, v125 offset0:32 offset1:33
	ds_write2_b32 v46, v122, v126 offset0:32 offset1:33
	ds_write2_b32 v47, v123, v127 offset0:32 offset1:33
	ds_write2_b32 v44, v128, v132 offset0:64 offset1:65
	ds_write2_b32 v45, v129, v133 offset0:64 offset1:65
	ds_write2_b32 v46, v130, v134 offset0:64 offset1:65
	ds_write2_b32 v47, v131, v135 offset0:64 offset1:65
	ds_write2_b32 v44, v136, v140 offset0:96 offset1:97
	ds_write2_b32 v45, v137, v141 offset0:96 offset1:97
	ds_write2_b32 v46, v138, v142 offset0:96 offset1:97
	ds_write2_b32 v47, v139, v143 offset0:96 offset1:97
	ds_read_b64 v[112:113], v52 offset:0
	ds_read_b64 v[114:115], v52 offset:512
	ds_read_b64 v[116:117], v52 offset:1024
	ds_read_b64 v[118:119], v52 offset:1536
	ds_read_b64 v[120:121], v52 offset:2048
	ds_read_b64 v[122:123], v52 offset:2560
	ds_read_b64 v[124:125], v52 offset:3072
	ds_read_b64 v[126:127], v52 offset:3584
	ds_read_b64 v[128:129], v52 offset:4096
	ds_read_b64 v[130:131], v52 offset:4608
	ds_read_b64 v[132:133], v52 offset:5120
	ds_read_b64 v[134:135], v52 offset:5632
	ds_read_b64 v[136:137], v52 offset:6144
	ds_read_b64 v[138:139], v52 offset:6656
	ds_read_b64 v[140:141], v52 offset:7168
	ds_read_b64 v[142:143], v52 offset:7680
	s_waitcnt lgkmcnt(15)
	v_fma_f32 v58, v36, v54, v112
	v_fma_f32 v59, v36, v55, v113
	v_fma_f32 v56, -v37, v55, v58
	v_fma_f32 v57, v37, v54, v59
	v_cvt_pk_bf16_f32 v62, v56, v57
	ds_write_b16 v60, v62 offset:4080
	ds_write_b16_d16_hi v60, v62 offset:4208
	s_waitcnt lgkmcnt(15)
	v_fma_f32 v58, v36, v56, v114
	v_fma_f32 v59, v36, v57, v115
	v_fma_f32 v54, -v37, v57, v58
	v_fma_f32 v55, v37, v56, v59
	v_cvt_pk_bf16_f32 v62, v54, v55
	ds_write_b16 v60, v62 offset:3808
	ds_write_b16_d16_hi v60, v62 offset:3936
	s_waitcnt lgkmcnt(15)
	v_fma_f32 v58, v36, v54, v116
	v_fma_f32 v59, v36, v55, v117
	v_fma_f32 v56, -v37, v55, v58
	v_fma_f32 v57, v37, v54, v59
	v_cvt_pk_bf16_f32 v62, v56, v57
	ds_write_b16 v60, v62 offset:3536
	ds_write_b16_d16_hi v60, v62 offset:3664
	s_waitcnt lgkmcnt(15)
	v_fma_f32 v58, v36, v56, v118
	v_fma_f32 v59, v36, v57, v119
	v_fma_f32 v54, -v37, v57, v58
	v_fma_f32 v55, v37, v56, v59
	v_cvt_pk_bf16_f32 v62, v54, v55
	ds_write_b16 v60, v62 offset:3264
	ds_write_b16_d16_hi v60, v62 offset:3392
	s_waitcnt lgkmcnt(15)
	v_fma_f32 v58, v36, v54, v120
	v_fma_f32 v59, v36, v55, v121
	v_fma_f32 v56, -v37, v55, v58
	v_fma_f32 v57, v37, v54, v59
	v_cvt_pk_bf16_f32 v62, v56, v57
	ds_write_b16 v60, v62 offset:2992
	ds_write_b16_d16_hi v60, v62 offset:3120
	s_waitcnt lgkmcnt(15)
	v_fma_f32 v58, v36, v56, v122
	v_fma_f32 v59, v36, v57, v123
	v_fma_f32 v54, -v37, v57, v58
	v_fma_f32 v55, v37, v56, v59
	v_cvt_pk_bf16_f32 v62, v54, v55
	ds_write_b16 v60, v62 offset:2720
	ds_write_b16_d16_hi v60, v62 offset:2848
	s_waitcnt lgkmcnt(15)
	v_fma_f32 v58, v36, v54, v124
	v_fma_f32 v59, v36, v55, v125
	v_fma_f32 v56, -v37, v55, v58
	v_fma_f32 v57, v37, v54, v59
	v_cvt_pk_bf16_f32 v62, v56, v57
	ds_write_b16 v60, v62 offset:2448
	ds_write_b16_d16_hi v60, v62 offset:2576
	s_waitcnt lgkmcnt(15)
; __device__ void phase_s5_pass2(CParams& p, int l, int item, char* smem) {
;     ...
;         float nr = A.x * hr - A.y * hi + bu[0];
;         float ni = A.x * hi + A.y * hr + bu[1];
;         hr = nr; hi = ni;
;         hs[tl * 136 + lane] = f2bf(hr);
;         hs[tl * 136 + 64 + lane] = f2bf(hi);
;       }
;       __syncthreads();
; #pragma unroll
;       for (int ks = 0; ks < 4; ks++) {
;         bf16x8 a = *(const bf16x8*)(hs + l15 * 136 + ks * 32 + lq * 8);
;         acc[sb] = __builtin_amdgcn_mfma_f32_16x16x32_bf16(a, cf[ks], acc[sb], 0, 0, 0);
;       }
;       __syncthreads();
;     }
;   }
;   asm volatile("s_nop 15\n\ts_nop 15" ::: "memory");
;   float dd = p.s5d[l * 256 + g * 16 + l15];
; #pragma unroll
;   for (int sb = 0; sb < 4; sb++)
; #pragma unroll
;     for (int j = 0; j < 4; j++) {
;       int t = sb * 16 + lq * 4 + j;
;       float y = acc[sb][j] + dd * us[t * 16 + l15];
	v_fma_f32 v58, v36, v56, v126
	v_fma_f32 v59, v36, v57, v127
	v_fma_f32 v54, -v37, v57, v58
	v_fma_f32 v55, v37, v56, v59
	v_cvt_pk_bf16_f32 v62, v54, v55
	ds_write_b16 v60, v62 offset:2176
	ds_write_b16_d16_hi v60, v62 offset:2304
	s_waitcnt lgkmcnt(15)
	v_fma_f32 v58, v36, v54, v128
	v_fma_f32 v59, v36, v55, v129
	v_fma_f32 v56, -v37, v55, v58
	v_fma_f32 v57, v37, v54, v59
	v_cvt_pk_bf16_f32 v62, v56, v57
	ds_write_b16 v60, v62 offset:1904
	ds_write_b16_d16_hi v60, v62 offset:2032
	s_waitcnt lgkmcnt(15)
	v_fma_f32 v58, v36, v56, v130
	v_fma_f32 v59, v36, v57, v131
	v_fma_f32 v54, -v37, v57, v58
	v_fma_f32 v55, v37, v56, v59
	v_cvt_pk_bf16_f32 v62, v54, v55
	ds_write_b16 v60, v62 offset:1632
	ds_write_b16_d16_hi v60, v62 offset:1760
	s_waitcnt lgkmcnt(15)
	v_fma_f32 v58, v36, v54, v132
	v_fma_f32 v59, v36, v55, v133
	v_fma_f32 v56, -v37, v55, v58
	v_fma_f32 v57, v37, v54, v59
	v_cvt_pk_bf16_f32 v62, v56, v57
	ds_write_b16 v60, v62 offset:1360
	ds_write_b16_d16_hi v60, v62 offset:1488
	s_waitcnt lgkmcnt(15)
	v_fma_f32 v58, v36, v56, v134
	v_fma_f32 v59, v36, v57, v135
	v_fma_f32 v54, -v37, v57, v58
	v_fma_f32 v55, v37, v56, v59
	v_cvt_pk_bf16_f32 v62, v54, v55
	ds_write_b16 v60, v62 offset:1088
	ds_write_b16_d16_hi v60, v62 offset:1216
	s_waitcnt lgkmcnt(15)
	v_fma_f32 v58, v36, v54, v136
	v_fma_f32 v59, v36, v55, v137
	v_fma_f32 v56, -v37, v55, v58
	v_fma_f32 v57, v37, v54, v59
	v_cvt_pk_bf16_f32 v62, v56, v57
	ds_write_b16 v60, v62 offset:816
	ds_write_b16_d16_hi v60, v62 offset:944
	s_waitcnt lgkmcnt(15)
	v_fma_f32 v58, v36, v56, v138
	v_fma_f32 v59, v36, v57, v139
	v_fma_f32 v54, -v37, v57, v58
	v_fma_f32 v55, v37, v56, v59
	v_cvt_pk_bf16_f32 v62, v54, v55
	ds_write_b16 v60, v62 offset:544
	ds_write_b16_d16_hi v60, v62 offset:672
	s_waitcnt lgkmcnt(15)
	v_fma_f32 v58, v36, v54, v140
	v_fma_f32 v59, v36, v55, v141
	v_fma_f32 v56, -v37, v55, v58
	v_fma_f32 v57, v37, v54, v59
	v_cvt_pk_bf16_f32 v62, v56, v57
	ds_write_b16 v60, v62 offset:272
	ds_write_b16_d16_hi v60, v62 offset:400
	s_waitcnt lgkmcnt(15)
	v_fma_f32 v58, v36, v56, v142
	v_fma_f32 v59, v36, v57, v143
	v_fma_f32 v54, -v37, v57, v58
	v_fma_f32 v55, v37, v56, v59
	v_cvt_pk_bf16_f32 v62, v54, v55
	ds_write_b16 v60, v62 offset:0
	ds_write_b16_d16_hi v60, v62 offset:128
	ds_read_b128 v[184:187], v61 offset:0
	ds_read_b128 v[188:191], v61 offset:64
	ds_read_b128 v[192:195], v61 offset:128
	ds_read_b128 v[196:199], v61 offset:192
	s_waitcnt lgkmcnt(0)
	v_mfma_f32_16x16x32_bf16 v[148:151], v[184:187], v[168:171], v[148:151]
	v_mfma_f32_16x16x32_bf16 v[148:151], v[188:191], v[172:175], v[148:151]
	v_mfma_f32_16x16x32_bf16 v[148:151], v[192:195], v[176:179], v[148:151]
	v_mfma_f32_16x16x32_bf16 v[148:151], v[196:199], v[180:183], v[148:151]
	s_load_dwordx2 s[92:93], s[44:45], 0x78
	s_lshl_b32 s20, s12, 8
	s_lshl_b32 s32, s2, 4
	s_add_u32 s20, s20, s32
	s_lshl_b32 s20, s20, 2
	v_lshlrev_b32_e32 v38, 2, v33
	s_waitcnt lgkmcnt(0)
	s_add_u32 s92, s92, s20
	s_addc_u32 s93, s93, 0
	global_load_dword v50, v38, s[92:93]
	global_load_dword v200, v63, s[6:7] offset:0
	global_load_dword v201, v63, s[6:7] offset:1024
	global_load_dword v202, v63, s[6:7] offset:2048
	global_load_dword v203, v63, s[6:7] offset:3072
	s_add_u32 s6, s6, 0x4000
	s_addc_u32 s7, s7, 0
	global_load_dword v204, v63, s[6:7] offset:0
	global_load_dword v205, v63, s[6:7] offset:1024
	global_load_dword v206, v63, s[6:7] offset:2048
	global_load_dword v207, v63, s[6:7] offset:3072
	s_add_u32 s6, s6, 0x4000
	s_addc_u32 s7, s7, 0
	global_load_dword v208, v63, s[6:7] offset:0
	global_load_dword v209, v63, s[6:7] offset:1024
	global_load_dword v210, v63, s[6:7] offset:2048
	global_load_dword v211, v63, s[6:7] offset:3072
	s_add_u32 s6, s6, 0x4000
	s_addc_u32 s7, s7, 0
	global_load_dword v212, v63, s[6:7] offset:0
	global_load_dword v213, v63, s[6:7] offset:1024
	global_load_dword v214, v63, s[6:7] offset:2048
	global_load_dword v215, v63, s[6:7] offset:3072
	s_nop 7
	s_waitcnt vmcnt(0)
; __device__ void phase_s5_pass2(CParams& p, int l, int item, char* smem) {
;     ...
;   float dd = p.s5d[l * 256 + g * 16 + l15];
; #pragma unroll
;   for (int sb = 0; sb < 4; sb++)
; #pragma unroll
;     for (int j = 0; j < 4; j++) {
;       int t = sb * 16 + lq * 4 + j;
;       float y = acc[sb][j] + dd * us[t * 16 + l15];
;       float z = 0.7978845608028654f * (y + 0.044715f * y * y * y);
;       float ge = y / (1.f + __expf(-2.f * z));
;       p.ys[(size_t)(tok0 + t) * 256 + g * 16 + l15] = f2bf(ge);
;     }
	v_fmac_f32_e32 v148, v50, v200
	v_mul_f32_e32 v200, v148, v148
	v_mul_f32_e32 v200, v200, v148
	v_mov_b32_e32 v39, 0x3d372713
	v_fma_f32 v200, v200, v39, v148
	v_mul_f32_e32 v200, 0xc0135761, v200
	v_exp_f32_e32 v200, v200
	s_nop 0
	v_add_f32_e32 v200, 1.0, v200
	v_rcp_f32_e32 v200, v200
	s_nop 0
	v_mul_f32_e32 v200, v200, v148
	v_cvt_pk_bf16_f32 v200, v200, v200
	global_store_short v48, v200, s[8:9] offset:0
	v_fmac_f32_e32 v149, v50, v201
	v_mul_f32_e32 v201, v149, v149
	v_mul_f32_e32 v201, v201, v149
	v_mov_b32_e32 v39, 0x3d372713
	v_fma_f32 v201, v201, v39, v149
	v_mul_f32_e32 v201, 0xc0135761, v201
	v_exp_f32_e32 v201, v201
	s_nop 0
	v_add_f32_e32 v201, 1.0, v201
	v_rcp_f32_e32 v201, v201
	s_nop 0
	v_mul_f32_e32 v201, v201, v149
	v_cvt_pk_bf16_f32 v201, v201, v201
	global_store_short v48, v201, s[8:9] offset:512
	v_fmac_f32_e32 v150, v50, v202
	v_mul_f32_e32 v202, v150, v150
	v_mul_f32_e32 v202, v202, v150
	v_mov_b32_e32 v39, 0x3d372713
	v_fma_f32 v202, v202, v39, v150
	v_mul_f32_e32 v202, 0xc0135761, v202
	v_exp_f32_e32 v202, v202
	s_nop 0
	v_add_f32_e32 v202, 1.0, v202
	v_rcp_f32_e32 v202, v202
	s_nop 0
	v_mul_f32_e32 v202, v202, v150
	v_cvt_pk_bf16_f32 v202, v202, v202
	global_store_short v48, v202, s[8:9] offset:1024
	v_fmac_f32_e32 v151, v50, v203
	v_mul_f32_e32 v203, v151, v151
	v_mul_f32_e32 v203, v203, v151
	v_mov_b32_e32 v39, 0x3d372713
	v_fma_f32 v203, v203, v39, v151
	v_mul_f32_e32 v203, 0xc0135761, v203
	v_exp_f32_e32 v203, v203
	s_nop 0
	v_add_f32_e32 v203, 1.0, v203
	v_rcp_f32_e32 v203, v203
	s_nop 0
	v_mul_f32_e32 v203, v203, v151
	v_cvt_pk_bf16_f32 v203, v203, v203
	global_store_short v48, v203, s[8:9] offset:1536
	s_add_u32 s8, s8, 0x2000
	s_addc_u32 s9, s9, 0
	v_fmac_f32_e32 v152, v50, v204
	v_mul_f32_e32 v204, v152, v152
	v_mul_f32_e32 v204, v204, v152
	v_mov_b32_e32 v39, 0x3d372713
	v_fma_f32 v204, v204, v39, v152
	v_mul_f32_e32 v204, 0xc0135761, v204
	v_exp_f32_e32 v204, v204
	s_nop 0
	v_add_f32_e32 v204, 1.0, v204
	v_rcp_f32_e32 v204, v204
	s_nop 0
	v_mul_f32_e32 v204, v204, v152
	v_cvt_pk_bf16_f32 v204, v204, v204
	global_store_short v48, v204, s[8:9] offset:0
	v_fmac_f32_e32 v153, v50, v205
	v_mul_f32_e32 v205, v153, v153
	v_mul_f32_e32 v205, v205, v153
	v_mov_b32_e32 v39, 0x3d372713
	v_fma_f32 v205, v205, v39, v153
	v_mul_f32_e32 v205, 0xc0135761, v205
	v_exp_f32_e32 v205, v205
	s_nop 0
	v_add_f32_e32 v205, 1.0, v205
	v_rcp_f32_e32 v205, v205
	s_nop 0
	v_mul_f32_e32 v205, v205, v153
	v_cvt_pk_bf16_f32 v205, v205, v205
	global_store_short v48, v205, s[8:9] offset:512
	v_fmac_f32_e32 v154, v50, v206
	v_mul_f32_e32 v206, v154, v154
	v_mul_f32_e32 v206, v206, v154
	v_mov_b32_e32 v39, 0x3d372713
	v_fma_f32 v206, v206, v39, v154
	v_mul_f32_e32 v206, 0xc0135761, v206
	v_exp_f32_e32 v206, v206
	s_nop 0
	v_add_f32_e32 v206, 1.0, v206
	v_rcp_f32_e32 v206, v206
	s_nop 0
	v_mul_f32_e32 v206, v206, v154
	v_cvt_pk_bf16_f32 v206, v206, v206
	global_store_short v48, v206, s[8:9] offset:1024
	v_fmac_f32_e32 v155, v50, v207
	v_mul_f32_e32 v207, v155, v155
	v_mul_f32_e32 v207, v207, v155
	v_mov_b32_e32 v39, 0x3d372713
	v_fma_f32 v207, v207, v39, v155
	v_mul_f32_e32 v207, 0xc0135761, v207
	v_exp_f32_e32 v207, v207
	s_nop 0
	v_add_f32_e32 v207, 1.0, v207
	v_rcp_f32_e32 v207, v207
	s_nop 0
	v_mul_f32_e32 v207, v207, v155
	v_cvt_pk_bf16_f32 v207, v207, v207
	global_store_short v48, v207, s[8:9] offset:1536
	s_add_u32 s8, s8, 0x2000
	s_addc_u32 s9, s9, 0
	v_fmac_f32_e32 v156, v50, v208
	v_mul_f32_e32 v208, v156, v156
	v_mul_f32_e32 v208, v208, v156
	v_mov_b32_e32 v39, 0x3d372713
	v_fma_f32 v208, v208, v39, v156
	v_mul_f32_e32 v208, 0xc0135761, v208
	v_exp_f32_e32 v208, v208
	s_nop 0
	v_add_f32_e32 v208, 1.0, v208
	v_rcp_f32_e32 v208, v208
	s_nop 0
	v_mul_f32_e32 v208, v208, v156
	v_cvt_pk_bf16_f32 v208, v208, v208
	global_store_short v48, v208, s[8:9] offset:0
	v_fmac_f32_e32 v157, v50, v209
	v_mul_f32_e32 v209, v157, v157
	v_mul_f32_e32 v209, v209, v157
	v_mov_b32_e32 v39, 0x3d372713
	v_fma_f32 v209, v209, v39, v157
	v_mul_f32_e32 v209, 0xc0135761, v209
	v_exp_f32_e32 v209, v209
	s_nop 0
	v_add_f32_e32 v209, 1.0, v209
	v_rcp_f32_e32 v209, v209
	s_nop 0
	v_mul_f32_e32 v209, v209, v157
	v_cvt_pk_bf16_f32 v209, v209, v209
	global_store_short v48, v209, s[8:9] offset:512
	v_fmac_f32_e32 v158, v50, v210
	v_mul_f32_e32 v210, v158, v158
	v_mul_f32_e32 v210, v210, v158
	v_mov_b32_e32 v39, 0x3d372713
	v_fma_f32 v210, v210, v39, v158
	v_mul_f32_e32 v210, 0xc0135761, v210
	v_exp_f32_e32 v210, v210
	s_nop 0
	v_add_f32_e32 v210, 1.0, v210
	v_rcp_f32_e32 v210, v210
	s_nop 0
	v_mul_f32_e32 v210, v210, v158
	v_cvt_pk_bf16_f32 v210, v210, v210
	global_store_short v48, v210, s[8:9] offset:1024
	v_fmac_f32_e32 v159, v50, v211
	v_mul_f32_e32 v211, v159, v159
	v_mul_f32_e32 v211, v211, v159
	v_mov_b32_e32 v39, 0x3d372713
	v_fma_f32 v211, v211, v39, v159
	v_mul_f32_e32 v211, 0xc0135761, v211
	v_exp_f32_e32 v211, v211
	s_nop 0
	v_add_f32_e32 v211, 1.0, v211
	v_rcp_f32_e32 v211, v211
	s_nop 0
	v_mul_f32_e32 v211, v211, v159
	v_cvt_pk_bf16_f32 v211, v211, v211
	global_store_short v48, v211, s[8:9] offset:1536
	s_add_u32 s8, s8, 0x2000
	s_addc_u32 s9, s9, 0
	v_fmac_f32_e32 v160, v50, v212
	v_mul_f32_e32 v212, v160, v160
	v_mul_f32_e32 v212, v212, v160
	v_mov_b32_e32 v39, 0x3d372713
	v_fma_f32 v212, v212, v39, v160
	v_mul_f32_e32 v212, 0xc0135761, v212
	v_exp_f32_e32 v212, v212
	s_nop 0
	v_add_f32_e32 v212, 1.0, v212
	v_rcp_f32_e32 v212, v212
	s_nop 0
	v_mul_f32_e32 v212, v212, v160
	v_cvt_pk_bf16_f32 v212, v212, v212
	global_store_short v48, v212, s[8:9] offset:0
	v_fmac_f32_e32 v161, v50, v213
	v_mul_f32_e32 v213, v161, v161
	v_mul_f32_e32 v213, v213, v161
	v_mov_b32_e32 v39, 0x3d372713
	v_fma_f32 v213, v213, v39, v161
	v_mul_f32_e32 v213, 0xc0135761, v213
	v_exp_f32_e32 v213, v213
	s_nop 0
	v_add_f32_e32 v213, 1.0, v213
	v_rcp_f32_e32 v213, v213
	s_nop 0
	v_mul_f32_e32 v213, v213, v161
	v_cvt_pk_bf16_f32 v213, v213, v213
	global_store_short v48, v213, s[8:9] offset:512
	v_fmac_f32_e32 v162, v50, v214
	v_mul_f32_e32 v214, v162, v162
	v_mul_f32_e32 v214, v214, v162
	v_mov_b32_e32 v39, 0x3d372713
	v_fma_f32 v214, v214, v39, v162
	v_mul_f32_e32 v214, 0xc0135761, v214
	v_exp_f32_e32 v214, v214
	s_nop 0
	v_add_f32_e32 v214, 1.0, v214
	v_rcp_f32_e32 v214, v214
	s_nop 0
	v_mul_f32_e32 v214, v214, v162
	v_cvt_pk_bf16_f32 v214, v214, v214
	global_store_short v48, v214, s[8:9] offset:1024
	v_fmac_f32_e32 v163, v50, v215
	v_mul_f32_e32 v215, v163, v163
	v_mul_f32_e32 v215, v215, v163
	v_mov_b32_e32 v39, 0x3d372713
	v_fma_f32 v215, v215, v39, v163
	v_mul_f32_e32 v215, 0xc0135761, v215
	v_exp_f32_e32 v215, v215
	s_nop 0
	v_add_f32_e32 v215, 1.0, v215
	v_rcp_f32_e32 v215, v215
	s_nop 0
	v_mul_f32_e32 v215, v215, v163
	v_cvt_pk_bf16_f32 v215, v215, v215
	global_store_short v48, v215, s[8:9] offset:1536
	s_waitcnt lgkmcnt(0)
	s_barrier
	s_branch .LBB0_686
